# stage loads of all five GEMM K-loops in SGPR-base form
# speedup vs baseline: 1.3454x; 1.0059x over previous
; #define PG8_STAGE(bufoff, gbase, voff) do { _Pragma("unroll") for (int _i = 0; _i < 2; ++_i) \
;         __builtin_amdgcn_global_load_lds((const unsigned*)((const char*)(gbase) + (voff)[_i]), (PG8_LAS unsigned*)(lds + (bufoff) + ldsw + _i * 8192), 16, 0, 0); } while (0)
; #define PG8_LDA(dst, b, h) do { _Pragma("unroll") for (int m = 0; m < 4; ++m) _Pragma("unroll") for (int k = 0; k < 2; ++k) dst[m][k] = *(const PG8_LAS bf16x8*)(lds + PG8_SA(b, h) + aoff + m * 2048 + k * 1024); } while (0)
; #define PG8_LDB(dst, b, h) do { _Pragma("unroll") for (int n = 0; n < 2; ++n) _Pragma("unroll") for (int k = 0; k < 2; ++k) dst[n][k] = *(const PG8_LAS bf16x8*)(lds + PG8_SB(b, h) + boff + n * 2048 + k * 1024); } while (0)
; #define PG8_WAIT_V(n) asm volatile("s_waitcnt vmcnt(" #n ")" ::: "memory")
; #define PG8_WAIT_L(n) asm volatile("s_waitcnt lgkmcnt(" #n ")" ::: "memory")
; #define PG8_BAR __builtin_amdgcn_s_barrier()
; #define PG8_SCHED __builtin_amdgcn_sched_barrier(0)
; template <class Epi, class Sched, bool ALIGN_EPI = false, bool SP2 = false, bool F8 = false>
; __device__ __forceinline__ void gemm_phase(PG8_LAS unsigned char* lds, const Gemm g, const Sched& S, const Epi& E) {
;     ...
;             PG8_LDB(B0, 0, 0); PG8_LDB(B1, 0, 1); PG8_SCHED; PG8_LDA(At, 0, 0); PG8_STAGE(PG8_SA(1, 1), a1 + hstepA, voffA);
;             PG8_WAIT_V(8); PG8_WAIT_L(0); PG8_BAR; PG8_MMA(0, 0, At, B0); PG8_MMA(0, 1, At, B1); PG8_BAR; PG8_SCHED;
;             PG8_LDA(At, 0, 1); PG8_STAGE(PG8_SB(0, 0), b2, voffB); PG8_STAGE(PG8_SB(0, 1), b2 + hstep, voffB); PG8_STAGE(PG8_SA(0, 0), a2, voffA);
;             PG8_WAIT_V(8); PG8_WAIT_L(0); PG8_BAR; PG8_MMA(1, 0, At, B0); PG8_MMA(1, 1, At, B1); PG8_BAR; PG8_SCHED;
.LBB0_255:
	ds_read_b128 v[130:133], v225
	ds_read_b128 v[134:137], v225 offset:1024
	ds_read_b128 v[138:141], v225 offset:2048
	ds_read_b128 v[142:145], v225 offset:3072
	ds_read_b128 v[146:149], v226
	ds_read_b128 v[150:153], v226 offset:1024
	ds_read_b128 v[154:157], v226 offset:2048
	ds_read_b128 v[158:161], v226 offset:3072
	s_add_u32 s24, s84, 0xfff80080
	s_addc_u32 s25, s85, -1
	s_cmp_eq_u32 s54, 28
	s_cselect_b32 s89, s13, s25
	s_cselect_b32 s88, s53, s24
	s_cselect_b32 s87, s77, vcc_hi
	s_cselect_b32 s86, s79, vcc_lo
	s_add_i32 m0, s95, 0xc000
	ds_read_b128 v[192:195], v227
	ds_read_b128 v[196:199], v227 offset:1024
	ds_read_b128 v[200:203], v227 offset:2048
	ds_read_b128 v[204:207], v227 offset:3072
	ds_read_b128 v[230:233], v227 offset:4096
	ds_read_b128 v[234:237], v227 offset:5120
	ds_read_b128 v[238:241], v227 offset:6144
	ds_read_b128 v[242:245], v227 offset:7168
	global_load_lds_dwordx4 v186, s[84:85]
	s_add_i32 m0, s95, 0xe000
	s_nop 0
	global_load_lds_dwordx4 v188, s[84:85]
	s_waitcnt vmcnt(8)
	s_waitcnt lgkmcnt(0)
	s_setprio 1
	s_waitcnt lgkmcnt(0)
	v_mfma_f32_16x16x32_bf16 v[126:129], v[130:133], v[192:195], v[126:129]
	v_mfma_f32_16x16x32_bf16 v[122:125], v[138:141], v[192:195], v[122:125]
	v_mfma_f32_16x16x32_bf16 v[110:113], v[130:133], v[200:203], v[110:113]
	v_mfma_f32_16x16x32_bf16 v[106:109], v[138:141], v[200:203], v[106:109]
	v_mfma_f32_16x16x32_bf16 v[94:97], v[130:133], v[230:233], v[94:97]
	v_mfma_f32_16x16x32_bf16 v[90:93], v[138:141], v[230:233], v[90:93]
	v_mfma_f32_16x16x32_bf16 v[78:81], v[130:133], v[238:241], v[78:81]
	v_mfma_f32_16x16x32_bf16 v[74:77], v[138:141], v[238:241], v[74:77]
	v_mfma_f32_16x16x32_bf16 v[126:129], v[134:137], v[196:199], v[126:129]
	v_mfma_f32_16x16x32_bf16 v[122:125], v[142:145], v[196:199], v[122:125]
	v_mfma_f32_16x16x32_bf16 v[110:113], v[134:137], v[204:207], v[110:113]
	v_mfma_f32_16x16x32_bf16 v[106:109], v[142:145], v[204:207], v[106:109]
	v_mfma_f32_16x16x32_bf16 v[94:97], v[134:137], v[234:237], v[94:97]
	v_mfma_f32_16x16x32_bf16 v[90:93], v[142:145], v[234:237], v[90:93]
	v_mfma_f32_16x16x32_bf16 v[78:81], v[134:137], v[242:245], v[78:81]
	v_mfma_f32_16x16x32_bf16 v[74:77], v[142:145], v[242:245], v[74:77]
	s_setprio 0
	s_setprio 1
	v_mfma_f32_16x16x32_bf16 v[118:121], v[146:149], v[192:195], v[118:121]
	v_mfma_f32_16x16x32_bf16 v[114:117], v[154:157], v[192:195], v[114:117]
	v_mfma_f32_16x16x32_bf16 v[102:105], v[146:149], v[200:203], v[102:105]
	v_mfma_f32_16x16x32_bf16 v[98:101], v[154:157], v[200:203], v[98:101]
	v_mfma_f32_16x16x32_bf16 v[86:89], v[146:149], v[230:233], v[86:89]
	v_mfma_f32_16x16x32_bf16 v[82:85], v[154:157], v[230:233], v[82:85]
	v_mfma_f32_16x16x32_bf16 v[70:73], v[146:149], v[238:241], v[70:73]
	v_mfma_f32_16x16x32_bf16 v[66:69], v[154:157], v[238:241], v[66:69]
	v_mfma_f32_16x16x32_bf16 v[118:121], v[150:153], v[196:199], v[118:121]
	v_mfma_f32_16x16x32_bf16 v[114:117], v[158:161], v[196:199], v[114:117]
	v_mfma_f32_16x16x32_bf16 v[102:105], v[150:153], v[204:207], v[102:105]
	v_mfma_f32_16x16x32_bf16 v[98:101], v[158:161], v[204:207], v[98:101]
	v_mfma_f32_16x16x32_bf16 v[86:89], v[150:153], v[234:237], v[86:89]
	v_mfma_f32_16x16x32_bf16 v[82:85], v[158:161], v[234:237], v[82:85]
	v_mfma_f32_16x16x32_bf16 v[70:73], v[150:153], v[242:245], v[70:73]
	v_mfma_f32_16x16x32_bf16 v[66:69], v[158:161], v[242:245], v[66:69]
	s_setprio 0
	s_barrier
	s_add_i32 s24, s45, s23
	s_mov_b32 m0, s24
	ds_read_b128 v[192:195], v227 offset:16384
	ds_read_b128 v[196:199], v227 offset:17408
	ds_read_b128 v[200:203], v227 offset:18432
	ds_read_b128 v[204:207], v227 offset:19456
	ds_read_b128 v[230:233], v227 offset:20480
	ds_read_b128 v[234:237], v227 offset:21504
	ds_read_b128 v[238:241], v227 offset:22528
	ds_read_b128 v[242:245], v227 offset:23552
	global_load_lds_dwordx4 v168, s[86:87]
	s_add_i32 m0, s24, 0x2000
	s_add_u32 s24, s86, 0x80000
	s_addc_u32 s25, s87, 0
	s_add_i32 s55, s33, s23
	global_load_lds_dwordx4 v164, s[86:87]
	s_mov_b32 m0, s55
	s_nop 0
	global_load_lds_dwordx4 v168, s[24:25]
	s_add_i32 m0, s55, 0x2000
	s_nop 0
	global_load_lds_dwordx4 v164, s[24:25]
	s_mov_b32 m0, s95
	s_nop 0
	global_load_lds_dwordx4 v170, s[88:89]
	s_mov_b32 m0, s96
	s_nop 0
	global_load_lds_dwordx4 v166, s[88:89]
	s_waitcnt vmcnt(8)
	s_waitcnt lgkmcnt(0)
	s_setprio 1
	s_waitcnt lgkmcnt(0)
	v_mfma_f32_16x16x32_bf16 v[62:65], v[130:133], v[192:195], v[62:65]
	v_mfma_f32_16x16x32_bf16 v[58:61], v[138:141], v[192:195], v[58:61]
	v_mfma_f32_16x16x32_bf16 v[46:49], v[130:133], v[200:203], v[46:49]
	v_mfma_f32_16x16x32_bf16 v[42:45], v[138:141], v[200:203], v[42:45]
	v_mfma_f32_16x16x32_bf16 v[30:33], v[130:133], v[230:233], v[30:33]
	v_mfma_f32_16x16x32_bf16 v[26:29], v[138:141], v[230:233], v[26:29]
	v_mfma_f32_16x16x32_bf16 v[14:17], v[130:133], v[238:241], v[14:17]
	v_mfma_f32_16x16x32_bf16 v[10:13], v[138:141], v[238:241], v[10:13]
	v_mfma_f32_16x16x32_bf16 v[62:65], v[134:137], v[196:199], v[62:65]
	v_mfma_f32_16x16x32_bf16 v[58:61], v[142:145], v[196:199], v[58:61]
	v_mfma_f32_16x16x32_bf16 v[46:49], v[134:137], v[204:207], v[46:49]
	v_mfma_f32_16x16x32_bf16 v[42:45], v[142:145], v[204:207], v[42:45]
	v_mfma_f32_16x16x32_bf16 v[30:33], v[134:137], v[234:237], v[30:33]
	v_mfma_f32_16x16x32_bf16 v[26:29], v[142:145], v[234:237], v[26:29]
	v_mfma_f32_16x16x32_bf16 v[14:17], v[134:137], v[242:245], v[14:17]
	v_mfma_f32_16x16x32_bf16 v[10:13], v[142:145], v[242:245], v[10:13]
	s_setprio 0
	s_setprio 1
	v_mfma_f32_16x16x32_bf16 v[54:57], v[146:149], v[192:195], v[54:57]
	v_mfma_f32_16x16x32_bf16 v[50:53], v[154:157], v[192:195], v[50:53]
	v_mfma_f32_16x16x32_bf16 v[38:41], v[146:149], v[200:203], v[38:41]
	v_mfma_f32_16x16x32_bf16 v[34:37], v[154:157], v[200:203], v[34:37]
	v_mfma_f32_16x16x32_bf16 v[22:25], v[146:149], v[230:233], v[22:25]
	v_mfma_f32_16x16x32_bf16 v[18:21], v[154:157], v[230:233], v[18:21]
	v_mfma_f32_16x16x32_bf16 v[6:9], v[146:149], v[238:241], v[6:9]
	v_mfma_f32_16x16x32_bf16 v[2:5], v[154:157], v[238:241], v[2:5]
	v_mfma_f32_16x16x32_bf16 v[54:57], v[150:153], v[196:199], v[54:57]
	v_mfma_f32_16x16x32_bf16 v[50:53], v[158:161], v[196:199], v[50:53]
	v_mfma_f32_16x16x32_bf16 v[38:41], v[150:153], v[204:207], v[38:41]
	v_mfma_f32_16x16x32_bf16 v[34:37], v[158:161], v[204:207], v[34:37]
	v_mfma_f32_16x16x32_bf16 v[22:25], v[150:153], v[234:237], v[22:25]
	v_mfma_f32_16x16x32_bf16 v[18:21], v[158:161], v[234:237], v[18:21]
	v_mfma_f32_16x16x32_bf16 v[6:9], v[150:153], v[242:245], v[6:9]
	v_mfma_f32_16x16x32_bf16 v[2:5], v[158:161], v[242:245], v[2:5]
	s_setprio 0
	s_barrier
; #define PG8_STAGE(bufoff, gbase, voff) do { _Pragma("unroll") for (int _i = 0; _i < 2; ++_i) \
;         __builtin_amdgcn_global_load_lds((const unsigned*)((const char*)(gbase) + (voff)[_i]), (PG8_LAS unsigned*)(lds + (bufoff) + ldsw + _i * 8192), 16, 0, 0); } while (0)
; #define PG8_LDA(dst, b, h) do { _Pragma("unroll") for (int m = 0; m < 4; ++m) _Pragma("unroll") for (int k = 0; k < 2; ++k) dst[m][k] = *(const PG8_LAS bf16x8*)(lds + PG8_SA(b, h) + aoff + m * 2048 + k * 1024); } while (0)
; #define PG8_LDB(dst, b, h) do { _Pragma("unroll") for (int n = 0; n < 2; ++n) _Pragma("unroll") for (int k = 0; k < 2; ++k) dst[n][k] = *(const PG8_LAS bf16x8*)(lds + PG8_SB(b, h) + boff + n * 2048 + k * 1024); } while (0)
; #define PG8_WAIT_V(n) asm volatile("s_waitcnt vmcnt(" #n ")" ::: "memory")
; #define PG8_WAIT_L(n) asm volatile("s_waitcnt lgkmcnt(" #n ")" ::: "memory")
; #define PG8_BAR __builtin_amdgcn_s_barrier()
; #define PG8_SCHED __builtin_amdgcn_sched_barrier(0)
; template <class Epi, class Sched, bool ALIGN_EPI = false, bool SP2 = false, bool F8 = false>
; __device__ __forceinline__ void gemm_phase(PG8_LAS unsigned char* lds, const Gemm g, const Sched& S, const Epi& E) {
;     ...
;             PG8_LDB(B0, 1, 0); PG8_LDB(B1, 1, 1); PG8_SCHED; PG8_LDA(At, 1, 0); PG8_STAGE(PG8_SA(0, 1), a2 + hstepA, voffA);
;             PG8_WAIT_V(8); PG8_WAIT_L(0); PG8_BAR; PG8_MMA(0, 0, At, B0); PG8_MMA(0, 1, At, B1); PG8_BAR; PG8_SCHED;
;             PG8_LDA(At, 1, 1); PG8_STAGE(PG8_SB(1, 0), b3, voffB); PG8_STAGE(PG8_SB(1, 1), b3 + hstep, voffB); PG8_STAGE(PG8_SA(1, 0), a3, voffA);
;             PG8_WAIT_V(8); PG8_WAIT_L(0); PG8_BAR; PG8_MMA(1, 0, At, B0); PG8_MMA(1, 1, At, B1); PG8_BAR; PG8_SCHED;
	s_add_i32 s55, 0, 0x18000
	s_add_i32 s36, 0, 0x1c000
	v_add_u32_e32 v142, s55, v222
	v_add_u32_e32 v158, s36, v222
	ds_read_b128 v[130:133], v142
	ds_read_b128 v[134:137], v142 offset:1024
	ds_read_b128 v[138:141], v142 offset:2048
	ds_read_b128 v[142:145], v142 offset:3072
	ds_read_b128 v[146:149], v158
	ds_read_b128 v[150:153], v158 offset:1024
	ds_read_b128 v[154:157], v158 offset:2048
	ds_read_b128 v[158:161], v158 offset:3072
	s_add_u32 s24, s88, 0x80000
	s_addc_u32 s25, s89, 0
	s_mov_b32 m0, s97
	ds_read_b128 v[192:195], v227 offset:32768
	ds_read_b128 v[196:199], v227 offset:33792
	ds_read_b128 v[200:203], v227 offset:34816
	ds_read_b128 v[204:207], v227 offset:35840
	ds_read_b128 v[230:233], v227 offset:36864
	ds_read_b128 v[234:237], v227 offset:37888
	ds_read_b128 v[238:241], v227 offset:38912
	ds_read_b128 v[242:245], v227 offset:39936
	global_load_lds_dwordx4 v170, s[24:25]
	s_mov_b32 m0, s28
	s_nop 0
	global_load_lds_dwordx4 v166, s[24:25]
	s_waitcnt vmcnt(8)
	s_waitcnt lgkmcnt(0)
	s_setprio 1
	s_waitcnt lgkmcnt(0)
	v_mfma_f32_16x16x32_bf16 v[126:129], v[130:133], v[192:195], v[126:129]
	v_mfma_f32_16x16x32_bf16 v[122:125], v[138:141], v[192:195], v[122:125]
	v_mfma_f32_16x16x32_bf16 v[110:113], v[130:133], v[200:203], v[110:113]
	v_mfma_f32_16x16x32_bf16 v[106:109], v[138:141], v[200:203], v[106:109]
	v_mfma_f32_16x16x32_bf16 v[94:97], v[130:133], v[230:233], v[94:97]
	v_mfma_f32_16x16x32_bf16 v[90:93], v[138:141], v[230:233], v[90:93]
	v_mfma_f32_16x16x32_bf16 v[78:81], v[130:133], v[238:241], v[78:81]
	v_mfma_f32_16x16x32_bf16 v[74:77], v[138:141], v[238:241], v[74:77]
	v_mfma_f32_16x16x32_bf16 v[126:129], v[134:137], v[196:199], v[126:129]
	v_mfma_f32_16x16x32_bf16 v[122:125], v[142:145], v[196:199], v[122:125]
	v_mfma_f32_16x16x32_bf16 v[110:113], v[134:137], v[204:207], v[110:113]
	v_mfma_f32_16x16x32_bf16 v[106:109], v[142:145], v[204:207], v[106:109]
	v_mfma_f32_16x16x32_bf16 v[94:97], v[134:137], v[234:237], v[94:97]
	v_mfma_f32_16x16x32_bf16 v[90:93], v[142:145], v[234:237], v[90:93]
	v_mfma_f32_16x16x32_bf16 v[78:81], v[134:137], v[242:245], v[78:81]
	v_mfma_f32_16x16x32_bf16 v[74:77], v[142:145], v[242:245], v[74:77]
	s_setprio 0
	s_setprio 1
	v_mfma_f32_16x16x32_bf16 v[118:121], v[146:149], v[192:195], v[118:121]
	v_mfma_f32_16x16x32_bf16 v[114:117], v[154:157], v[192:195], v[114:117]
	v_mfma_f32_16x16x32_bf16 v[102:105], v[146:149], v[200:203], v[102:105]
	v_mfma_f32_16x16x32_bf16 v[98:101], v[154:157], v[200:203], v[98:101]
	v_mfma_f32_16x16x32_bf16 v[86:89], v[146:149], v[230:233], v[86:89]
	v_mfma_f32_16x16x32_bf16 v[82:85], v[154:157], v[230:233], v[82:85]
	v_mfma_f32_16x16x32_bf16 v[70:73], v[146:149], v[238:241], v[70:73]
	v_mfma_f32_16x16x32_bf16 v[66:69], v[154:157], v[238:241], v[66:69]
	v_mfma_f32_16x16x32_bf16 v[118:121], v[150:153], v[196:199], v[118:121]
	v_mfma_f32_16x16x32_bf16 v[114:117], v[158:161], v[196:199], v[114:117]
	v_mfma_f32_16x16x32_bf16 v[102:105], v[150:153], v[204:207], v[102:105]
	v_mfma_f32_16x16x32_bf16 v[98:101], v[158:161], v[204:207], v[98:101]
	v_mfma_f32_16x16x32_bf16 v[86:89], v[150:153], v[234:237], v[86:89]
	v_mfma_f32_16x16x32_bf16 v[82:85], v[158:161], v[234:237], v[82:85]
	v_mfma_f32_16x16x32_bf16 v[70:73], v[150:153], v[242:245], v[70:73]
	v_mfma_f32_16x16x32_bf16 v[66:69], v[158:161], v[242:245], v[66:69]
	s_setprio 0
	s_barrier
	s_add_i32 s24, s55, s23
	s_mov_b32 m0, s24
	ds_read_b128 v[192:195], v227 offset:49152
	ds_read_b128 v[196:199], v227 offset:50176
	ds_read_b128 v[200:203], v227 offset:51200
	ds_read_b128 v[204:207], v227 offset:52224
	ds_read_b128 v[230:233], v227 offset:53248
	ds_read_b128 v[234:237], v227 offset:54272
	ds_read_b128 v[238:241], v227 offset:55296
	ds_read_b128 v[242:245], v227 offset:56320
	s_add_u32 s98, s86, 0x80
	s_addc_u32 s99, s87, 0
	global_load_lds_dwordx4 v168, s[98:99]
	s_add_i32 m0, s24, 0x2000
	s_add_u32 s24, s86, 0x80080
	s_addc_u32 s25, s87, 0
	s_add_i32 s36, s36, s23
	s_add_u32 s100, s86, 0x80
	s_addc_u32 s101, s87, 0
	global_load_lds_dwordx4 v164, s[100:101]
	s_mov_b32 m0, s36
	s_nop 0
	global_load_lds_dwordx4 v168, s[24:25]
	s_add_i32 m0, s36, 0x2000
	s_nop 0
	global_load_lds_dwordx4 v164, s[24:25]
	s_mov_b32 m0, s15
	s_nop 0
	s_add_u32 s98, s88, 0x80
	s_addc_u32 s99, s89, 0
	global_load_lds_dwordx4 v170, s[98:99]
	s_mov_b32 m0, s26
	s_nop 0
	s_add_u32 s100, s88, 0x80
	s_addc_u32 s101, s89, 0
	global_load_lds_dwordx4 v166, s[100:101]
	s_waitcnt vmcnt(8)
	s_waitcnt lgkmcnt(0)
	s_setprio 1
	s_waitcnt lgkmcnt(0)
	v_mfma_f32_16x16x32_bf16 v[62:65], v[130:133], v[192:195], v[62:65]
	v_mfma_f32_16x16x32_bf16 v[58:61], v[138:141], v[192:195], v[58:61]
	v_mfma_f32_16x16x32_bf16 v[46:49], v[130:133], v[200:203], v[46:49]
	v_mfma_f32_16x16x32_bf16 v[42:45], v[138:141], v[200:203], v[42:45]
	v_mfma_f32_16x16x32_bf16 v[30:33], v[130:133], v[230:233], v[30:33]
	v_mfma_f32_16x16x32_bf16 v[26:29], v[138:141], v[230:233], v[26:29]
	v_mfma_f32_16x16x32_bf16 v[14:17], v[130:133], v[238:241], v[14:17]
	v_mfma_f32_16x16x32_bf16 v[10:13], v[138:141], v[238:241], v[10:13]
	v_mfma_f32_16x16x32_bf16 v[62:65], v[134:137], v[196:199], v[62:65]
	v_mfma_f32_16x16x32_bf16 v[58:61], v[142:145], v[196:199], v[58:61]
	v_mfma_f32_16x16x32_bf16 v[46:49], v[134:137], v[204:207], v[46:49]
	v_mfma_f32_16x16x32_bf16 v[42:45], v[142:145], v[204:207], v[42:45]
	v_mfma_f32_16x16x32_bf16 v[30:33], v[134:137], v[234:237], v[30:33]
	v_mfma_f32_16x16x32_bf16 v[26:29], v[142:145], v[234:237], v[26:29]
	v_mfma_f32_16x16x32_bf16 v[14:17], v[134:137], v[242:245], v[14:17]
	v_mfma_f32_16x16x32_bf16 v[10:13], v[142:145], v[242:245], v[10:13]
	s_setprio 0
	s_setprio 1
	v_mfma_f32_16x16x32_bf16 v[54:57], v[146:149], v[192:195], v[54:57]
	v_mfma_f32_16x16x32_bf16 v[50:53], v[154:157], v[192:195], v[50:53]
	v_mfma_f32_16x16x32_bf16 v[38:41], v[146:149], v[200:203], v[38:41]
	v_mfma_f32_16x16x32_bf16 v[34:37], v[154:157], v[200:203], v[34:37]
	v_mfma_f32_16x16x32_bf16 v[22:25], v[146:149], v[230:233], v[22:25]
	v_mfma_f32_16x16x32_bf16 v[18:21], v[154:157], v[230:233], v[18:21]
	v_mfma_f32_16x16x32_bf16 v[6:9], v[146:149], v[238:241], v[6:9]
	v_mfma_f32_16x16x32_bf16 v[2:5], v[154:157], v[238:241], v[2:5]
	v_mfma_f32_16x16x32_bf16 v[54:57], v[150:153], v[196:199], v[54:57]
	v_mfma_f32_16x16x32_bf16 v[50:53], v[158:161], v[196:199], v[50:53]
	v_mfma_f32_16x16x32_bf16 v[38:41], v[150:153], v[204:207], v[38:41]
	v_mfma_f32_16x16x32_bf16 v[34:37], v[158:161], v[204:207], v[34:37]
	v_mfma_f32_16x16x32_bf16 v[22:25], v[150:153], v[234:237], v[22:25]
	v_mfma_f32_16x16x32_bf16 v[18:21], v[158:161], v[234:237], v[18:21]
	v_mfma_f32_16x16x32_bf16 v[6:9], v[150:153], v[242:245], v[6:9]
	v_mfma_f32_16x16x32_bf16 v[2:5], v[158:161], v[242:245], v[2:5]
	s_setprio 0
	s_barrier
	s_add_i32 s54, s54, 2
	s_add_u32 s84, s84, 0x100
	s_addc_u32 s85, s85, 0
	s_add_u32 vcc_lo, vcc_lo, 0x100
	s_addc_u32 vcc_hi, vcc_hi, 0
	s_cmp_gt_u32 s54, 29
	s_cbranch_scc0 .LBB0_255
	s_branch .Lk0_exit
; #define PG8_STAGE(bufoff, gbase, voff) do { _Pragma("unroll") for (int _i = 0; _i < 2; ++_i) \
;         __builtin_amdgcn_global_load_lds((const unsigned*)((const char*)(gbase) + (voff)[_i]), (PG8_LAS unsigned*)(lds + (bufoff) + ldsw + _i * 8192), 16, 0, 0); } while (0)
; #define PG8_LDA(dst, b, h) do { _Pragma("unroll") for (int m = 0; m < 4; ++m) _Pragma("unroll") for (int k = 0; k < 2; ++k) dst[m][k] = *(const PG8_LAS bf16x8*)(lds + PG8_SA(b, h) + aoff + m * 2048 + k * 1024); } while (0)
; #define PG8_LDB(dst, b, h) do { _Pragma("unroll") for (int n = 0; n < 2; ++n) _Pragma("unroll") for (int k = 0; k < 2; ++k) dst[n][k] = *(const PG8_LAS bf16x8*)(lds + PG8_SB(b, h) + boff + n * 2048 + k * 1024); } while (0)
; #define PG8_WAIT_V(n) asm volatile("s_waitcnt vmcnt(" #n ")" ::: "memory")
; #define PG8_WAIT_L(n) asm volatile("s_waitcnt lgkmcnt(" #n ")" ::: "memory")
; #define PG8_BAR __builtin_amdgcn_s_barrier()
; #define PG8_SCHED __builtin_amdgcn_sched_barrier(0)
; template <class Epi, class Sched, bool ALIGN_EPI = false, bool SP2 = false, bool F8 = false>
; __device__ __forceinline__ void gemm_phase(PG8_LAS unsigned char* lds, const Gemm g, const Sched& S, const Epi& E) {
;     ...
;             PG8_LDB(B0, 0, 0); PG8_LDB(B1, 0, 1); PG8_SCHED; PG8_LDA(At, 0, 0); PG8_STAGE(PG8_SA(1, 1), a1 + hstepA, voffA);
;             PG8_WAIT_V(8); PG8_WAIT_L(0); PG8_BAR; PG8_MMA(0, 0, At, B0); PG8_MMA(0, 1, At, B1); PG8_BAR; PG8_SCHED;
;             PG8_LDA(At, 0, 1); PG8_STAGE(PG8_SB(0, 0), b2, voffB); PG8_STAGE(PG8_SB(0, 1), b2 + hstep, voffB); PG8_STAGE(PG8_SA(0, 0), a2, voffA);
;             PG8_WAIT_V(8); PG8_WAIT_L(0); PG8_BAR; PG8_MMA(1, 0, At, B0); PG8_MMA(1, 1, At, B1); PG8_BAR; PG8_SCHED;
.Lk0_Y:
	ds_read_b128 v[130:133], v225
	ds_read_b128 v[134:137], v225 offset:1024
	ds_read_b128 v[138:141], v225 offset:2048
	ds_read_b128 v[142:145], v225 offset:3072
	ds_read_b128 v[146:149], v226
	ds_read_b128 v[150:153], v226 offset:1024
	ds_read_b128 v[154:157], v226 offset:2048
	ds_read_b128 v[158:161], v226 offset:3072
	s_add_u32 s24, s84, 0xfff80080
	s_addc_u32 s25, s85, -1
	s_cmp_eq_u32 s54, 28
	s_cselect_b32 s89, s13, s25
	s_cselect_b32 s88, s53, s24
	s_cselect_b32 s87, s77, vcc_hi
	s_cselect_b32 s86, s79, vcc_lo
	s_add_i32 m0, s95, 0xc000
	ds_read_b128 v[192:195], v227
	ds_read_b128 v[196:199], v227 offset:1024
	ds_read_b128 v[200:203], v227 offset:2048
	ds_read_b128 v[204:207], v227 offset:3072
	ds_read_b128 v[230:233], v227 offset:4096
	ds_read_b128 v[234:237], v227 offset:5120
	ds_read_b128 v[238:241], v227 offset:6144
	ds_read_b128 v[242:245], v227 offset:7168
	global_load_lds_dwordx4 v186, s[84:85]
	s_add_i32 m0, s95, 0xe000
	s_nop 0
	global_load_lds_dwordx4 v188, s[84:85]
	s_waitcnt vmcnt(8)
	s_waitcnt lgkmcnt(0)
	s_barrier
	s_setprio 3
	s_waitcnt lgkmcnt(0)
	v_mfma_f32_16x16x32_bf16 v[126:129], v[130:133], v[192:195], v[126:129]
	v_mfma_f32_16x16x32_bf16 v[122:125], v[138:141], v[192:195], v[122:125]
	v_mfma_f32_16x16x32_bf16 v[110:113], v[130:133], v[200:203], v[110:113]
	v_mfma_f32_16x16x32_bf16 v[106:109], v[138:141], v[200:203], v[106:109]
	v_mfma_f32_16x16x32_bf16 v[94:97], v[130:133], v[230:233], v[94:97]
	v_mfma_f32_16x16x32_bf16 v[90:93], v[138:141], v[230:233], v[90:93]
	v_mfma_f32_16x16x32_bf16 v[78:81], v[130:133], v[238:241], v[78:81]
	v_mfma_f32_16x16x32_bf16 v[74:77], v[138:141], v[238:241], v[74:77]
	v_mfma_f32_16x16x32_bf16 v[126:129], v[134:137], v[196:199], v[126:129]
	v_mfma_f32_16x16x32_bf16 v[122:125], v[142:145], v[196:199], v[122:125]
	v_mfma_f32_16x16x32_bf16 v[110:113], v[134:137], v[204:207], v[110:113]
	v_mfma_f32_16x16x32_bf16 v[106:109], v[142:145], v[204:207], v[106:109]
	v_mfma_f32_16x16x32_bf16 v[94:97], v[134:137], v[234:237], v[94:97]
	v_mfma_f32_16x16x32_bf16 v[90:93], v[142:145], v[234:237], v[90:93]
	v_mfma_f32_16x16x32_bf16 v[78:81], v[134:137], v[242:245], v[78:81]
	v_mfma_f32_16x16x32_bf16 v[74:77], v[142:145], v[242:245], v[74:77]
	s_setprio 0
	s_setprio 3
	v_mfma_f32_16x16x32_bf16 v[118:121], v[146:149], v[192:195], v[118:121]
	v_mfma_f32_16x16x32_bf16 v[114:117], v[154:157], v[192:195], v[114:117]
	v_mfma_f32_16x16x32_bf16 v[102:105], v[146:149], v[200:203], v[102:105]
	v_mfma_f32_16x16x32_bf16 v[98:101], v[154:157], v[200:203], v[98:101]
	v_mfma_f32_16x16x32_bf16 v[86:89], v[146:149], v[230:233], v[86:89]
	v_mfma_f32_16x16x32_bf16 v[82:85], v[154:157], v[230:233], v[82:85]
	v_mfma_f32_16x16x32_bf16 v[70:73], v[146:149], v[238:241], v[70:73]
	v_mfma_f32_16x16x32_bf16 v[66:69], v[154:157], v[238:241], v[66:69]
	v_mfma_f32_16x16x32_bf16 v[118:121], v[150:153], v[196:199], v[118:121]
	v_mfma_f32_16x16x32_bf16 v[114:117], v[158:161], v[196:199], v[114:117]
	v_mfma_f32_16x16x32_bf16 v[102:105], v[150:153], v[204:207], v[102:105]
	v_mfma_f32_16x16x32_bf16 v[98:101], v[158:161], v[204:207], v[98:101]
	v_mfma_f32_16x16x32_bf16 v[86:89], v[150:153], v[234:237], v[86:89]
	v_mfma_f32_16x16x32_bf16 v[82:85], v[158:161], v[234:237], v[82:85]
	v_mfma_f32_16x16x32_bf16 v[70:73], v[150:153], v[242:245], v[70:73]
	v_mfma_f32_16x16x32_bf16 v[66:69], v[158:161], v[242:245], v[66:69]
	s_setprio 0
	s_add_i32 s24, s45, s23
	s_mov_b32 m0, s24
	ds_read_b128 v[192:195], v227 offset:16384
	ds_read_b128 v[196:199], v227 offset:17408
	ds_read_b128 v[200:203], v227 offset:18432
	ds_read_b128 v[204:207], v227 offset:19456
	ds_read_b128 v[230:233], v227 offset:20480
	ds_read_b128 v[234:237], v227 offset:21504
	ds_read_b128 v[238:241], v227 offset:22528
	ds_read_b128 v[242:245], v227 offset:23552
	global_load_lds_dwordx4 v168, s[86:87]
	s_add_i32 m0, s24, 0x2000
	s_add_u32 s24, s86, 0x80000
	s_addc_u32 s25, s87, 0
	s_add_i32 s55, s33, s23
	global_load_lds_dwordx4 v164, s[86:87]
	s_mov_b32 m0, s55
	s_nop 0
	global_load_lds_dwordx4 v168, s[24:25]
	s_add_i32 m0, s55, 0x2000
	s_nop 0
	global_load_lds_dwordx4 v164, s[24:25]
	s_mov_b32 m0, s95
	s_nop 0
	global_load_lds_dwordx4 v170, s[88:89]
	s_mov_b32 m0, s96
	s_nop 0
	global_load_lds_dwordx4 v166, s[88:89]
	s_waitcnt vmcnt(8)
	s_waitcnt lgkmcnt(0)
	s_barrier
; #define PG8_STAGE(bufoff, gbase, voff) do { _Pragma("unroll") for (int _i = 0; _i < 2; ++_i) \
;         __builtin_amdgcn_global_load_lds((const unsigned*)((const char*)(gbase) + (voff)[_i]), (PG8_LAS unsigned*)(lds + (bufoff) + ldsw + _i * 8192), 16, 0, 0); } while (0)
; #define PG8_LDA(dst, b, h) do { _Pragma("unroll") for (int m = 0; m < 4; ++m) _Pragma("unroll") for (int k = 0; k < 2; ++k) dst[m][k] = *(const PG8_LAS bf16x8*)(lds + PG8_SA(b, h) + aoff + m * 2048 + k * 1024); } while (0)
; #define PG8_LDB(dst, b, h) do { _Pragma("unroll") for (int n = 0; n < 2; ++n) _Pragma("unroll") for (int k = 0; k < 2; ++k) dst[n][k] = *(const PG8_LAS bf16x8*)(lds + PG8_SB(b, h) + boff + n * 2048 + k * 1024); } while (0)
; #define PG8_WAIT_V(n) asm volatile("s_waitcnt vmcnt(" #n ")" ::: "memory")
; #define PG8_WAIT_L(n) asm volatile("s_waitcnt lgkmcnt(" #n ")" ::: "memory")
; #define PG8_BAR __builtin_amdgcn_s_barrier()
; #define PG8_SCHED __builtin_amdgcn_sched_barrier(0)
; template <class Epi, class Sched, bool ALIGN_EPI = false, bool SP2 = false, bool F8 = false>
; __device__ __forceinline__ void gemm_phase(PG8_LAS unsigned char* lds, const Gemm g, const Sched& S, const Epi& E) {
;     ...
;             PG8_WAIT_V(8); PG8_WAIT_L(0); PG8_BAR; PG8_MMA(1, 0, At, B0); PG8_MMA(1, 1, At, B1); PG8_BAR; PG8_SCHED;
;             PG8_LDB(B0, 1, 0); PG8_LDB(B1, 1, 1); PG8_SCHED; PG8_LDA(At, 1, 0); PG8_STAGE(PG8_SA(0, 1), a2 + hstepA, voffA);
;             PG8_WAIT_V(8); PG8_WAIT_L(0); PG8_BAR; PG8_MMA(0, 0, At, B0); PG8_MMA(0, 1, At, B1); PG8_BAR; PG8_SCHED;
;             PG8_LDA(At, 1, 1); PG8_STAGE(PG8_SB(1, 0), b3, voffB); PG8_STAGE(PG8_SB(1, 1), b3 + hstep, voffB); PG8_STAGE(PG8_SA(1, 0), a3, voffA);
	s_setprio 3
	s_waitcnt lgkmcnt(0)
	v_mfma_f32_16x16x32_bf16 v[62:65], v[130:133], v[192:195], v[62:65]
	v_mfma_f32_16x16x32_bf16 v[58:61], v[138:141], v[192:195], v[58:61]
	v_mfma_f32_16x16x32_bf16 v[46:49], v[130:133], v[200:203], v[46:49]
	v_mfma_f32_16x16x32_bf16 v[42:45], v[138:141], v[200:203], v[42:45]
	v_mfma_f32_16x16x32_bf16 v[30:33], v[130:133], v[230:233], v[30:33]
	v_mfma_f32_16x16x32_bf16 v[26:29], v[138:141], v[230:233], v[26:29]
	v_mfma_f32_16x16x32_bf16 v[14:17], v[130:133], v[238:241], v[14:17]
	v_mfma_f32_16x16x32_bf16 v[10:13], v[138:141], v[238:241], v[10:13]
	v_mfma_f32_16x16x32_bf16 v[62:65], v[134:137], v[196:199], v[62:65]
	v_mfma_f32_16x16x32_bf16 v[58:61], v[142:145], v[196:199], v[58:61]
	v_mfma_f32_16x16x32_bf16 v[46:49], v[134:137], v[204:207], v[46:49]
	v_mfma_f32_16x16x32_bf16 v[42:45], v[142:145], v[204:207], v[42:45]
	v_mfma_f32_16x16x32_bf16 v[30:33], v[134:137], v[234:237], v[30:33]
	v_mfma_f32_16x16x32_bf16 v[26:29], v[142:145], v[234:237], v[26:29]
	v_mfma_f32_16x16x32_bf16 v[14:17], v[134:137], v[242:245], v[14:17]
	v_mfma_f32_16x16x32_bf16 v[10:13], v[142:145], v[242:245], v[10:13]
	s_setprio 0
	s_setprio 3
	v_mfma_f32_16x16x32_bf16 v[54:57], v[146:149], v[192:195], v[54:57]
	v_mfma_f32_16x16x32_bf16 v[50:53], v[154:157], v[192:195], v[50:53]
	v_mfma_f32_16x16x32_bf16 v[38:41], v[146:149], v[200:203], v[38:41]
	v_mfma_f32_16x16x32_bf16 v[34:37], v[154:157], v[200:203], v[34:37]
	v_mfma_f32_16x16x32_bf16 v[22:25], v[146:149], v[230:233], v[22:25]
	v_mfma_f32_16x16x32_bf16 v[18:21], v[154:157], v[230:233], v[18:21]
	v_mfma_f32_16x16x32_bf16 v[6:9], v[146:149], v[238:241], v[6:9]
	v_mfma_f32_16x16x32_bf16 v[2:5], v[154:157], v[238:241], v[2:5]
	v_mfma_f32_16x16x32_bf16 v[54:57], v[150:153], v[196:199], v[54:57]
	v_mfma_f32_16x16x32_bf16 v[50:53], v[158:161], v[196:199], v[50:53]
	v_mfma_f32_16x16x32_bf16 v[38:41], v[150:153], v[204:207], v[38:41]
	v_mfma_f32_16x16x32_bf16 v[34:37], v[158:161], v[204:207], v[34:37]
	v_mfma_f32_16x16x32_bf16 v[22:25], v[150:153], v[234:237], v[22:25]
	v_mfma_f32_16x16x32_bf16 v[18:21], v[158:161], v[234:237], v[18:21]
	v_mfma_f32_16x16x32_bf16 v[6:9], v[150:153], v[242:245], v[6:9]
	v_mfma_f32_16x16x32_bf16 v[2:5], v[158:161], v[242:245], v[2:5]
	s_setprio 0
	s_add_i32 s55, 0, 0x18000
	s_add_i32 s36, 0, 0x1c000
	v_add_u32_e32 v142, s55, v222
	v_add_u32_e32 v158, s36, v222
	ds_read_b128 v[130:133], v142
	ds_read_b128 v[134:137], v142 offset:1024
	ds_read_b128 v[138:141], v142 offset:2048
	ds_read_b128 v[142:145], v142 offset:3072
	ds_read_b128 v[146:149], v158
	ds_read_b128 v[150:153], v158 offset:1024
	ds_read_b128 v[154:157], v158 offset:2048
	ds_read_b128 v[158:161], v158 offset:3072
	s_add_u32 s24, s88, 0x80000
	s_addc_u32 s25, s89, 0
	s_mov_b32 m0, s97
	ds_read_b128 v[192:195], v227 offset:32768
	ds_read_b128 v[196:199], v227 offset:33792
	ds_read_b128 v[200:203], v227 offset:34816
	ds_read_b128 v[204:207], v227 offset:35840
	ds_read_b128 v[230:233], v227 offset:36864
	ds_read_b128 v[234:237], v227 offset:37888
	ds_read_b128 v[238:241], v227 offset:38912
	ds_read_b128 v[242:245], v227 offset:39936
	global_load_lds_dwordx4 v170, s[24:25]
	s_mov_b32 m0, s28
	s_nop 0
	global_load_lds_dwordx4 v166, s[24:25]
	s_waitcnt vmcnt(8)
	s_waitcnt lgkmcnt(0)
	s_barrier
; #define PG8_STAGE(bufoff, gbase, voff) do { _Pragma("unroll") for (int _i = 0; _i < 2; ++_i) \
;         __builtin_amdgcn_global_load_lds((const unsigned*)((const char*)(gbase) + (voff)[_i]), (PG8_LAS unsigned*)(lds + (bufoff) + ldsw + _i * 8192), 16, 0, 0); } while (0)
; #define PG8_LDA(dst, b, h) do { _Pragma("unroll") for (int m = 0; m < 4; ++m) _Pragma("unroll") for (int k = 0; k < 2; ++k) dst[m][k] = *(const PG8_LAS bf16x8*)(lds + PG8_SA(b, h) + aoff + m * 2048 + k * 1024); } while (0)
; #define PG8_WAIT_V(n) asm volatile("s_waitcnt vmcnt(" #n ")" ::: "memory")
; #define PG8_WAIT_L(n) asm volatile("s_waitcnt lgkmcnt(" #n ")" ::: "memory")
; #define PG8_BAR __builtin_amdgcn_s_barrier()
; #define PG8_SCHED __builtin_amdgcn_sched_barrier(0)
; template <class Epi, class Sched, bool ALIGN_EPI = false, bool SP2 = false, bool F8 = false>
; __device__ __forceinline__ void gemm_phase(PG8_LAS unsigned char* lds, const Gemm g, const Sched& S, const Epi& E) {
;     ...
;             PG8_WAIT_V(8); PG8_WAIT_L(0); PG8_BAR; PG8_MMA(0, 0, At, B0); PG8_MMA(0, 1, At, B1); PG8_BAR; PG8_SCHED;
;             PG8_LDA(At, 1, 1); PG8_STAGE(PG8_SB(1, 0), b3, voffB); PG8_STAGE(PG8_SB(1, 1), b3 + hstep, voffB); PG8_STAGE(PG8_SA(1, 0), a3, voffA);
;             PG8_WAIT_V(8); PG8_WAIT_L(0); PG8_BAR; PG8_MMA(1, 0, At, B0); PG8_MMA(1, 1, At, B1); PG8_BAR; PG8_SCHED;
	s_setprio 3
	s_waitcnt lgkmcnt(0)
	v_mfma_f32_16x16x32_bf16 v[126:129], v[130:133], v[192:195], v[126:129]
	v_mfma_f32_16x16x32_bf16 v[122:125], v[138:141], v[192:195], v[122:125]
	v_mfma_f32_16x16x32_bf16 v[110:113], v[130:133], v[200:203], v[110:113]
	v_mfma_f32_16x16x32_bf16 v[106:109], v[138:141], v[200:203], v[106:109]
	v_mfma_f32_16x16x32_bf16 v[94:97], v[130:133], v[230:233], v[94:97]
	v_mfma_f32_16x16x32_bf16 v[90:93], v[138:141], v[230:233], v[90:93]
	v_mfma_f32_16x16x32_bf16 v[78:81], v[130:133], v[238:241], v[78:81]
	v_mfma_f32_16x16x32_bf16 v[74:77], v[138:141], v[238:241], v[74:77]
	v_mfma_f32_16x16x32_bf16 v[126:129], v[134:137], v[196:199], v[126:129]
	v_mfma_f32_16x16x32_bf16 v[122:125], v[142:145], v[196:199], v[122:125]
	v_mfma_f32_16x16x32_bf16 v[110:113], v[134:137], v[204:207], v[110:113]
	v_mfma_f32_16x16x32_bf16 v[106:109], v[142:145], v[204:207], v[106:109]
	v_mfma_f32_16x16x32_bf16 v[94:97], v[134:137], v[234:237], v[94:97]
	v_mfma_f32_16x16x32_bf16 v[90:93], v[142:145], v[234:237], v[90:93]
	v_mfma_f32_16x16x32_bf16 v[78:81], v[134:137], v[242:245], v[78:81]
	v_mfma_f32_16x16x32_bf16 v[74:77], v[142:145], v[242:245], v[74:77]
	s_setprio 0
	s_setprio 3
	v_mfma_f32_16x16x32_bf16 v[118:121], v[146:149], v[192:195], v[118:121]
	v_mfma_f32_16x16x32_bf16 v[114:117], v[154:157], v[192:195], v[114:117]
	v_mfma_f32_16x16x32_bf16 v[102:105], v[146:149], v[200:203], v[102:105]
	v_mfma_f32_16x16x32_bf16 v[98:101], v[154:157], v[200:203], v[98:101]
	v_mfma_f32_16x16x32_bf16 v[86:89], v[146:149], v[230:233], v[86:89]
	v_mfma_f32_16x16x32_bf16 v[82:85], v[154:157], v[230:233], v[82:85]
	v_mfma_f32_16x16x32_bf16 v[70:73], v[146:149], v[238:241], v[70:73]
	v_mfma_f32_16x16x32_bf16 v[66:69], v[154:157], v[238:241], v[66:69]
	v_mfma_f32_16x16x32_bf16 v[118:121], v[150:153], v[196:199], v[118:121]
	v_mfma_f32_16x16x32_bf16 v[114:117], v[158:161], v[196:199], v[114:117]
	v_mfma_f32_16x16x32_bf16 v[102:105], v[150:153], v[204:207], v[102:105]
	v_mfma_f32_16x16x32_bf16 v[98:101], v[158:161], v[204:207], v[98:101]
	v_mfma_f32_16x16x32_bf16 v[86:89], v[150:153], v[234:237], v[86:89]
	v_mfma_f32_16x16x32_bf16 v[82:85], v[158:161], v[234:237], v[82:85]
	v_mfma_f32_16x16x32_bf16 v[70:73], v[150:153], v[242:245], v[70:73]
	v_mfma_f32_16x16x32_bf16 v[66:69], v[158:161], v[242:245], v[66:69]
	s_setprio 0
	s_add_i32 s24, s55, s23
	s_mov_b32 m0, s24
	ds_read_b128 v[192:195], v227 offset:49152
	ds_read_b128 v[196:199], v227 offset:50176
	ds_read_b128 v[200:203], v227 offset:51200
	ds_read_b128 v[204:207], v227 offset:52224
	ds_read_b128 v[230:233], v227 offset:53248
	ds_read_b128 v[234:237], v227 offset:54272
	ds_read_b128 v[238:241], v227 offset:55296
	ds_read_b128 v[242:245], v227 offset:56320
	s_add_u32 s98, s86, 0x80
	s_addc_u32 s99, s87, 0
	global_load_lds_dwordx4 v168, s[98:99]
	s_add_i32 m0, s24, 0x2000
	s_add_u32 s24, s86, 0x80080
	s_addc_u32 s25, s87, 0
	s_add_i32 s36, s36, s23
	s_add_u32 s100, s86, 0x80
	s_addc_u32 s101, s87, 0
	global_load_lds_dwordx4 v164, s[100:101]
	s_mov_b32 m0, s36
	s_nop 0
	global_load_lds_dwordx4 v168, s[24:25]
	s_add_i32 m0, s36, 0x2000
	s_nop 0
	global_load_lds_dwordx4 v164, s[24:25]
	s_mov_b32 m0, s15
	s_nop 0
	s_add_u32 s98, s88, 0x80
	s_addc_u32 s99, s89, 0
	global_load_lds_dwordx4 v170, s[98:99]
	s_mov_b32 m0, s26
	s_nop 0
	s_add_u32 s100, s88, 0x80
	s_addc_u32 s101, s89, 0
	global_load_lds_dwordx4 v166, s[100:101]
	s_waitcnt vmcnt(8)
	s_waitcnt lgkmcnt(0)
	s_barrier
	s_setprio 3
	s_waitcnt lgkmcnt(0)
	v_mfma_f32_16x16x32_bf16 v[62:65], v[130:133], v[192:195], v[62:65]
	v_mfma_f32_16x16x32_bf16 v[58:61], v[138:141], v[192:195], v[58:61]
	v_mfma_f32_16x16x32_bf16 v[46:49], v[130:133], v[200:203], v[46:49]
	v_mfma_f32_16x16x32_bf16 v[42:45], v[138:141], v[200:203], v[42:45]
	v_mfma_f32_16x16x32_bf16 v[30:33], v[130:133], v[230:233], v[30:33]
	v_mfma_f32_16x16x32_bf16 v[26:29], v[138:141], v[230:233], v[26:29]
	v_mfma_f32_16x16x32_bf16 v[14:17], v[130:133], v[238:241], v[14:17]
	v_mfma_f32_16x16x32_bf16 v[10:13], v[138:141], v[238:241], v[10:13]
	v_mfma_f32_16x16x32_bf16 v[62:65], v[134:137], v[196:199], v[62:65]
	v_mfma_f32_16x16x32_bf16 v[58:61], v[142:145], v[196:199], v[58:61]
	v_mfma_f32_16x16x32_bf16 v[46:49], v[134:137], v[204:207], v[46:49]
	v_mfma_f32_16x16x32_bf16 v[42:45], v[142:145], v[204:207], v[42:45]
	v_mfma_f32_16x16x32_bf16 v[30:33], v[134:137], v[234:237], v[30:33]
	v_mfma_f32_16x16x32_bf16 v[26:29], v[142:145], v[234:237], v[26:29]
	v_mfma_f32_16x16x32_bf16 v[14:17], v[134:137], v[242:245], v[14:17]
	v_mfma_f32_16x16x32_bf16 v[10:13], v[142:145], v[242:245], v[10:13]
	s_setprio 0
	s_setprio 3
	v_mfma_f32_16x16x32_bf16 v[54:57], v[146:149], v[192:195], v[54:57]
	v_mfma_f32_16x16x32_bf16 v[50:53], v[154:157], v[192:195], v[50:53]
	v_mfma_f32_16x16x32_bf16 v[38:41], v[146:149], v[200:203], v[38:41]
	v_mfma_f32_16x16x32_bf16 v[34:37], v[154:157], v[200:203], v[34:37]
	v_mfma_f32_16x16x32_bf16 v[22:25], v[146:149], v[230:233], v[22:25]
	v_mfma_f32_16x16x32_bf16 v[18:21], v[154:157], v[230:233], v[18:21]
	v_mfma_f32_16x16x32_bf16 v[6:9], v[146:149], v[238:241], v[6:9]
	v_mfma_f32_16x16x32_bf16 v[2:5], v[154:157], v[238:241], v[2:5]
	v_mfma_f32_16x16x32_bf16 v[54:57], v[150:153], v[196:199], v[54:57]
	v_mfma_f32_16x16x32_bf16 v[50:53], v[158:161], v[196:199], v[50:53]
	v_mfma_f32_16x16x32_bf16 v[38:41], v[150:153], v[204:207], v[38:41]
	v_mfma_f32_16x16x32_bf16 v[34:37], v[158:161], v[204:207], v[34:37]
	v_mfma_f32_16x16x32_bf16 v[22:25], v[150:153], v[234:237], v[22:25]
	v_mfma_f32_16x16x32_bf16 v[18:21], v[158:161], v[234:237], v[18:21]
	v_mfma_f32_16x16x32_bf16 v[6:9], v[150:153], v[242:245], v[6:9]
	v_mfma_f32_16x16x32_bf16 v[2:5], v[158:161], v[242:245], v[2:5]
	s_setprio 0
	s_add_i32 s54, s54, 2
	s_add_u32 s84, s84, 0x100
	s_addc_u32 s85, s85, 0
	s_add_u32 vcc_lo, vcc_lo, 0x100
	s_addc_u32 vcc_hi, vcc_hi, 0
	s_cmp_gt_u32 s54, 29
	s_cbranch_scc0 .Lk0_Y

; #define PG8_STAGE(bufoff, gbase, voff) do { _Pragma("unroll") for (int _i = 0; _i < 2; ++_i) \
;         __builtin_amdgcn_global_load_lds((const unsigned*)((const char*)(gbase) + (voff)[_i]), (PG8_LAS unsigned*)(lds + (bufoff) + ldsw + _i * 8192), 16, 0, 0); } while (0)
; #define PG8_LDA(dst, b, h) do { _Pragma("unroll") for (int m = 0; m < 4; ++m) _Pragma("unroll") for (int k = 0; k < 2; ++k) dst[m][k] = *(const PG8_LAS bf16x8*)(lds + PG8_SA(b, h) + aoff + m * 2048 + k * 1024); } while (0)
; #define PG8_LDB(dst, b, h) do { _Pragma("unroll") for (int n = 0; n < 2; ++n) _Pragma("unroll") for (int k = 0; k < 2; ++k) dst[n][k] = *(const PG8_LAS bf16x8*)(lds + PG8_SB(b, h) + boff + n * 2048 + k * 1024); } while (0)
; #define PG8_WAIT_V(n) asm volatile("s_waitcnt vmcnt(" #n ")" ::: "memory")
; #define PG8_WAIT_L(n) asm volatile("s_waitcnt lgkmcnt(" #n ")" ::: "memory")
; #define PG8_BAR __builtin_amdgcn_s_barrier()
; #define PG8_SCHED __builtin_amdgcn_sched_barrier(0)
; template <class Epi, class Sched, bool ALIGN_EPI = false, bool SP2 = false, bool F8 = false>
; __device__ __forceinline__ void gemm_phase(PG8_LAS unsigned char* lds, const Gemm g, const Sched& S, const Epi& E) {
;     ...
;             PG8_LDB(B0, 0, 0); PG8_LDB(B1, 0, 1); PG8_SCHED; PG8_LDA(At, 0, 0); PG8_STAGE(PG8_SA(1, 1), a1 + hstepA, voffA);
;             PG8_WAIT_V(8); PG8_WAIT_L(0); PG8_BAR; PG8_MMA(0, 0, At, B0); PG8_MMA(0, 1, At, B1); PG8_BAR; PG8_SCHED;
;             PG8_LDA(At, 0, 1); PG8_STAGE(PG8_SB(0, 0), b2, voffB); PG8_STAGE(PG8_SB(0, 1), b2 + hstep, voffB); PG8_STAGE(PG8_SA(0, 0), a2, voffA);
;             PG8_WAIT_V(8); PG8_WAIT_L(0); PG8_BAR; PG8_MMA(1, 0, At, B0); PG8_MMA(1, 1, At, B1); PG8_BAR; PG8_SCHED;
;             PG8_LDB(B0, 1, 0); PG8_LDB(B1, 1, 1); PG8_SCHED; PG8_LDA(At, 1, 0); PG8_STAGE(PG8_SA(0, 1), a2 + hstepA, voffA);
;             PG8_WAIT_V(8); PG8_WAIT_L(0); PG8_BAR; PG8_MMA(0, 0, At, B0); PG8_MMA(0, 1, At, B1); PG8_BAR; PG8_SCHED;
;             PG8_LDA(At, 1, 1); PG8_STAGE(PG8_SB(1, 0), b3, voffB); PG8_STAGE(PG8_SB(1, 1), b3 + hstep, voffB); PG8_STAGE(PG8_SA(1, 0), a3, voffA);
;             PG8_WAIT_V(8); PG8_WAIT_L(0); PG8_BAR; PG8_MMA(1, 0, At, B0); PG8_MMA(1, 1, At, B1); PG8_BAR; PG8_SCHED;
.LBB0_291:
	ds_read_b128 v[26:29], v195
	ds_read_b128 v[30:33], v195 offset:1024
	ds_read_b128 v[18:21], v195 offset:2048
	ds_read_b128 v[22:25], v195 offset:3072
	ds_read_b128 v[10:13], v196
	ds_read_b128 v[14:17], v196 offset:1024
	ds_read_b128 v[2:5], v196 offset:2048
	ds_read_b128 v[6:9], v196 offset:3072
	s_add_u32 s24, s72, 0xfffc0080
	s_addc_u32 s25, s73, -1
	s_cmp_eq_u32 s87, 12
	s_cselect_b32 s77, s7, s25
	s_cselect_b32 s76, s65, s24
	s_cselect_b32 s75, s63, s86
	s_cselect_b32 s74, s71, s85
	s_add_i32 m0, s26, 0xc000
	ds_read_b128 v[182:185], v197
	ds_read_b128 v[186:189], v197 offset:1024
	ds_read_b128 v[200:203], v197 offset:2048
	ds_read_b128 v[204:207], v197 offset:3072
	ds_read_b128 v[208:211], v197 offset:4096
	ds_read_b128 v[212:215], v197 offset:5120
	ds_read_b128 v[218:221], v197 offset:6144
	ds_read_b128 v[222:225], v197 offset:7168
	global_load_lds_dwordx4 v178, s[72:73]
	s_add_i32 m0, s26, 0xe000
	s_nop 0
	global_load_lds_dwordx4 v180, s[72:73]
	s_waitcnt vmcnt(8)
	s_waitcnt lgkmcnt(0)
	s_setprio 1
	s_waitcnt lgkmcnt(0)
	v_mfma_f32_16x16x128_f8f6f4 v[158:161], v[26:33], v[182:189], v[158:161]
	v_mfma_f32_16x16x128_f8f6f4 v[154:157], v[18:25], v[182:189], v[154:157]
	v_mfma_f32_16x16x128_f8f6f4 v[142:145], v[26:33], v[200:207], v[142:145]
	v_mfma_f32_16x16x128_f8f6f4 v[138:141], v[18:25], v[200:207], v[138:141]
	v_mfma_f32_16x16x128_f8f6f4 v[126:129], v[26:33], v[208:215], v[126:129]
	v_mfma_f32_16x16x128_f8f6f4 v[122:125], v[18:25], v[208:215], v[122:125]
	v_mfma_f32_16x16x128_f8f6f4 v[110:113], v[26:33], v[218:225], v[110:113]
	v_mfma_f32_16x16x128_f8f6f4 v[106:109], v[18:25], v[218:225], v[106:109]
	s_setprio 0
	s_setprio 1
	v_mfma_f32_16x16x128_f8f6f4 v[150:153], v[10:17], v[182:189], v[150:153]
	v_mfma_f32_16x16x128_f8f6f4 v[146:149], v[2:9], v[182:189], v[146:149]
	v_mfma_f32_16x16x128_f8f6f4 v[134:137], v[10:17], v[200:207], v[134:137]
	v_mfma_f32_16x16x128_f8f6f4 v[130:133], v[2:9], v[200:207], v[130:133]
	v_mfma_f32_16x16x128_f8f6f4 v[118:121], v[10:17], v[208:215], v[118:121]
	v_mfma_f32_16x16x128_f8f6f4 v[114:117], v[2:9], v[208:215], v[114:117]
	v_mfma_f32_16x16x128_f8f6f4 v[102:105], v[10:17], v[218:225], v[102:105]
	v_mfma_f32_16x16x128_f8f6f4 v[98:101], v[2:9], v[218:225], v[98:101]
	s_setprio 0
	s_barrier
	s_add_i32 s24, s81, s14
	s_mov_b32 m0, s24
	ds_read_b128 v[200:203], v197 offset:16384
	ds_read_b128 v[204:207], v197 offset:17408
	ds_read_b128 v[208:211], v197 offset:18432
	ds_read_b128 v[212:215], v197 offset:19456
	ds_read_b128 v[218:221], v197 offset:20480
	ds_read_b128 v[222:225], v197 offset:21504
	ds_read_b128 v[226:229], v197 offset:22528
	ds_read_b128 v[230:233], v197 offset:23552
	global_load_lds_dwordx4 v166, s[74:75]
	s_add_i32 m0, s24, 0x2000
	s_add_u32 s24, s74, 0x40000
	s_addc_u32 s25, s75, 0
	s_add_i32 s36, s82, s14
	global_load_lds_dwordx4 v170, s[74:75]
	s_mov_b32 m0, s36
	s_nop 0
	global_load_lds_dwordx4 v166, s[24:25]
	s_add_i32 m0, s36, 0x2000
	s_nop 0
	global_load_lds_dwordx4 v170, s[24:25]
	s_mov_b32 m0, s26
	s_nop 0
	global_load_lds_dwordx4 v164, s[76:77]
	s_mov_b32 m0, s27
	s_nop 0
	global_load_lds_dwordx4 v168, s[76:77]
	s_waitcnt vmcnt(8)
	s_waitcnt lgkmcnt(0)
	s_setprio 1
	s_waitcnt lgkmcnt(0)
	v_mfma_f32_16x16x128_f8f6f4 v[94:97], v[26:33], v[200:207], v[94:97]
	v_mfma_f32_16x16x128_f8f6f4 v[90:93], v[18:25], v[200:207], v[90:93]
	v_mfma_f32_16x16x128_f8f6f4 v[78:81], v[26:33], v[208:215], v[78:81]
	v_mfma_f32_16x16x128_f8f6f4 v[74:77], v[18:25], v[208:215], v[74:77]
	v_mfma_f32_16x16x128_f8f6f4 v[62:65], v[26:33], v[218:225], v[62:65]
	v_mfma_f32_16x16x128_f8f6f4 v[58:61], v[18:25], v[218:225], v[58:61]
	v_mfma_f32_16x16x128_f8f6f4 v[46:49], v[26:33], v[226:233], v[46:49]
	v_mfma_f32_16x16x128_f8f6f4 v[42:45], v[18:25], v[226:233], v[42:45]
	s_setprio 0
	s_setprio 1
	v_mfma_f32_16x16x128_f8f6f4 v[86:89], v[10:17], v[200:207], v[86:89]
	v_mfma_f32_16x16x128_f8f6f4 v[82:85], v[2:9], v[200:207], v[82:85]
	v_mfma_f32_16x16x128_f8f6f4 v[70:73], v[10:17], v[208:215], v[70:73]
	v_mfma_f32_16x16x128_f8f6f4 v[66:69], v[2:9], v[208:215], v[66:69]
	v_mfma_f32_16x16x128_f8f6f4 v[54:57], v[10:17], v[218:225], v[54:57]
	v_mfma_f32_16x16x128_f8f6f4 v[50:53], v[2:9], v[218:225], v[50:53]
	v_mfma_f32_16x16x128_f8f6f4 v[38:41], v[10:17], v[226:233], v[38:41]
	v_mfma_f32_16x16x128_f8f6f4 v[34:37], v[2:9], v[226:233], v[34:37]
	s_setprio 0
	s_barrier
	s_add_i32 s36, 0, 0x18000
	s_add_i32 s37, 0, 0x1c000
	v_add_u32_e32 v14, s36, v190
	v_add_u32_e32 v30, s37, v190
	ds_read_b128 v[2:5], v14
	ds_read_b128 v[6:9], v14 offset:1024
	ds_read_b128 v[10:13], v14 offset:2048
	ds_read_b128 v[14:17], v14 offset:3072
	ds_read_b128 v[18:21], v30
	ds_read_b128 v[22:25], v30 offset:1024
	ds_read_b128 v[26:29], v30 offset:2048
	ds_read_b128 v[30:33], v30 offset:3072
	s_add_u32 s24, s76, 0x40000
	s_addc_u32 s25, s77, 0
	s_mov_b32 m0, s28
	ds_read_b128 v[200:203], v197 offset:32768
	ds_read_b128 v[204:207], v197 offset:33792
	ds_read_b128 v[208:211], v197 offset:34816
	ds_read_b128 v[212:215], v197 offset:35840
	ds_read_b128 v[218:221], v197 offset:36864
	ds_read_b128 v[222:225], v197 offset:37888
	ds_read_b128 v[226:229], v197 offset:38912
	ds_read_b128 v[230:233], v197 offset:39936
	global_load_lds_dwordx4 v164, s[24:25]
	s_mov_b32 m0, s29
	s_nop 0
	global_load_lds_dwordx4 v168, s[24:25]
	s_waitcnt vmcnt(8)
	s_waitcnt lgkmcnt(0)
	s_setprio 1
	s_waitcnt lgkmcnt(0)
	v_mfma_f32_16x16x128_f8f6f4 v[158:161], v[2:9], v[200:207], v[158:161]
	v_mfma_f32_16x16x128_f8f6f4 v[154:157], v[10:17], v[200:207], v[154:157]
	v_mfma_f32_16x16x128_f8f6f4 v[142:145], v[2:9], v[208:215], v[142:145]
	v_mfma_f32_16x16x128_f8f6f4 v[138:141], v[10:17], v[208:215], v[138:141]
	v_mfma_f32_16x16x128_f8f6f4 v[126:129], v[2:9], v[218:225], v[126:129]
	v_mfma_f32_16x16x128_f8f6f4 v[122:125], v[10:17], v[218:225], v[122:125]
	v_mfma_f32_16x16x128_f8f6f4 v[110:113], v[2:9], v[226:233], v[110:113]
	v_mfma_f32_16x16x128_f8f6f4 v[106:109], v[10:17], v[226:233], v[106:109]
	s_setprio 0
	s_setprio 1
	v_mfma_f32_16x16x128_f8f6f4 v[150:153], v[18:25], v[200:207], v[150:153]
	v_mfma_f32_16x16x128_f8f6f4 v[146:149], v[26:33], v[200:207], v[146:149]
	v_mfma_f32_16x16x128_f8f6f4 v[134:137], v[18:25], v[208:215], v[134:137]
	v_mfma_f32_16x16x128_f8f6f4 v[130:133], v[26:33], v[208:215], v[130:133]
	v_mfma_f32_16x16x128_f8f6f4 v[118:121], v[18:25], v[218:225], v[118:121]
	v_mfma_f32_16x16x128_f8f6f4 v[114:117], v[26:33], v[218:225], v[114:117]
	v_mfma_f32_16x16x128_f8f6f4 v[102:105], v[18:25], v[226:233], v[102:105]
	v_mfma_f32_16x16x128_f8f6f4 v[98:101], v[26:33], v[226:233], v[98:101]
	s_setprio 0
	s_barrier
; #define PG8_STAGE(bufoff, gbase, voff) do { _Pragma("unroll") for (int _i = 0; _i < 2; ++_i) \
;         __builtin_amdgcn_global_load_lds((const unsigned*)((const char*)(gbase) + (voff)[_i]), (PG8_LAS unsigned*)(lds + (bufoff) + ldsw + _i * 8192), 16, 0, 0); } while (0)
; #define PG8_LDA(dst, b, h) do { _Pragma("unroll") for (int m = 0; m < 4; ++m) _Pragma("unroll") for (int k = 0; k < 2; ++k) dst[m][k] = *(const PG8_LAS bf16x8*)(lds + PG8_SA(b, h) + aoff + m * 2048 + k * 1024); } while (0)
; #define PG8_LDB(dst, b, h) do { _Pragma("unroll") for (int n = 0; n < 2; ++n) _Pragma("unroll") for (int k = 0; k < 2; ++k) dst[n][k] = *(const PG8_LAS bf16x8*)(lds + PG8_SB(b, h) + boff + n * 2048 + k * 1024); } while (0)
; #define PG8_WAIT_V(n) asm volatile("s_waitcnt vmcnt(" #n ")" ::: "memory")
; #define PG8_WAIT_L(n) asm volatile("s_waitcnt lgkmcnt(" #n ")" ::: "memory")
; #define PG8_BAR __builtin_amdgcn_s_barrier()
; #define PG8_SCHED __builtin_amdgcn_sched_barrier(0)
; template <class Epi, class Sched, bool ALIGN_EPI = false, bool SP2 = false, bool F8 = false>
; __device__ __forceinline__ void gemm_phase(PG8_LAS unsigned char* lds, const Gemm g, const Sched& S, const Epi& E) {
;     ...
;             PG8_LDB(B0, 0, 0); PG8_LDB(B1, 0, 1); PG8_SCHED; PG8_LDA(At, 0, 0); PG8_STAGE(PG8_SA(1, 1), a1 + hstepA, voffA);
;             PG8_WAIT_V(8); PG8_WAIT_L(0); PG8_BAR; PG8_MMA(0, 0, At, B0); PG8_MMA(0, 1, At, B1); PG8_BAR; PG8_SCHED;
;             PG8_LDA(At, 0, 1); PG8_STAGE(PG8_SB(0, 0), b2, voffB); PG8_STAGE(PG8_SB(0, 1), b2 + hstep, voffB); PG8_STAGE(PG8_SA(0, 0), a2, voffA);
;     ...
;             PG8_LDA(At, 1, 1); PG8_STAGE(PG8_SB(1, 0), b3, voffB); PG8_STAGE(PG8_SB(1, 1), b3 + hstep, voffB); PG8_STAGE(PG8_SA(1, 0), a3, voffA);
;             PG8_WAIT_V(8); PG8_WAIT_L(0); PG8_BAR; PG8_MMA(1, 0, At, B0); PG8_MMA(1, 1, At, B1); PG8_BAR; PG8_SCHED;
	s_add_i32 s24, s36, s14
	s_mov_b32 m0, s24
	ds_read_b128 v[200:203], v197 offset:49152
	ds_read_b128 v[204:207], v197 offset:50176
	ds_read_b128 v[208:211], v197 offset:51200
	ds_read_b128 v[212:215], v197 offset:52224
	ds_read_b128 v[218:221], v197 offset:53248
	ds_read_b128 v[222:225], v197 offset:54272
	ds_read_b128 v[226:229], v197 offset:55296
	ds_read_b128 v[230:233], v197 offset:56320
	s_add_u32 s98, s74, 0x80
	s_addc_u32 s99, s75, 0
	global_load_lds_dwordx4 v166, s[98:99]
	s_add_i32 m0, s24, 0x2000
	s_add_u32 s24, s74, 0x40080
	s_addc_u32 s25, s75, 0
	s_add_i32 s36, s37, s14
	s_add_u32 s100, s74, 0x80
	s_addc_u32 s101, s75, 0
	global_load_lds_dwordx4 v170, s[100:101]
	s_mov_b32 m0, s36
	s_nop 0
	global_load_lds_dwordx4 v166, s[24:25]
	s_add_i32 m0, s36, 0x2000
	s_nop 0
	global_load_lds_dwordx4 v170, s[24:25]
	s_mov_b32 m0, s45
	s_nop 0
	s_add_u32 s98, s76, 0x80
	s_addc_u32 s99, s77, 0
	global_load_lds_dwordx4 v164, s[98:99]
	s_mov_b32 m0, s78
	s_nop 0
	s_add_u32 s100, s76, 0x80
	s_addc_u32 s101, s77, 0
	global_load_lds_dwordx4 v168, s[100:101]
	s_waitcnt vmcnt(8)
	s_waitcnt lgkmcnt(0)
	s_setprio 1
	s_waitcnt lgkmcnt(0)
	v_mfma_f32_16x16x128_f8f6f4 v[94:97], v[2:9], v[200:207], v[94:97]
	v_mfma_f32_16x16x128_f8f6f4 v[90:93], v[10:17], v[200:207], v[90:93]
	v_mfma_f32_16x16x128_f8f6f4 v[78:81], v[2:9], v[208:215], v[78:81]
	v_mfma_f32_16x16x128_f8f6f4 v[74:77], v[10:17], v[208:215], v[74:77]
	v_mfma_f32_16x16x128_f8f6f4 v[62:65], v[2:9], v[218:225], v[62:65]
	v_mfma_f32_16x16x128_f8f6f4 v[58:61], v[10:17], v[218:225], v[58:61]
	v_mfma_f32_16x16x128_f8f6f4 v[46:49], v[2:9], v[226:233], v[46:49]
	v_mfma_f32_16x16x128_f8f6f4 v[42:45], v[10:17], v[226:233], v[42:45]
	s_setprio 0
	s_setprio 1
	v_mfma_f32_16x16x128_f8f6f4 v[86:89], v[18:25], v[200:207], v[86:89]
	v_mfma_f32_16x16x128_f8f6f4 v[82:85], v[26:33], v[200:207], v[82:85]
	v_mfma_f32_16x16x128_f8f6f4 v[70:73], v[18:25], v[208:215], v[70:73]
	v_mfma_f32_16x16x128_f8f6f4 v[66:69], v[26:33], v[208:215], v[66:69]
	v_mfma_f32_16x16x128_f8f6f4 v[54:57], v[18:25], v[218:225], v[54:57]
	v_mfma_f32_16x16x128_f8f6f4 v[50:53], v[26:33], v[218:225], v[50:53]
	v_mfma_f32_16x16x128_f8f6f4 v[38:41], v[18:25], v[226:233], v[38:41]
	v_mfma_f32_16x16x128_f8f6f4 v[34:37], v[26:33], v[226:233], v[34:37]
	s_setprio 0
	s_barrier
	s_add_i32 s87, s87, 2
	s_add_u32 s72, s72, 0x100
	s_addc_u32 s73, s73, 0
	s_add_u32 s85, s85, 0x100
	s_addc_u32 s86, s86, 0
	s_cmp_gt_u32 s87, 13
	s_cbranch_scc0 .LBB0_291
	s_branch .Lk1_exit
.Lk1_Y:
	ds_read_b128 v[26:29], v195
	ds_read_b128 v[30:33], v195 offset:1024
	ds_read_b128 v[18:21], v195 offset:2048
	ds_read_b128 v[22:25], v195 offset:3072
	ds_read_b128 v[10:13], v196
	ds_read_b128 v[14:17], v196 offset:1024
	ds_read_b128 v[2:5], v196 offset:2048
	ds_read_b128 v[6:9], v196 offset:3072
	s_add_u32 s24, s72, 0xfffc0080
	s_addc_u32 s25, s73, -1
	s_cmp_eq_u32 s87, 12
	s_cselect_b32 s77, s7, s25
	s_cselect_b32 s76, s65, s24
	s_cselect_b32 s75, s63, s86
	s_cselect_b32 s74, s71, s85
	s_add_i32 m0, s26, 0xc000
	ds_read_b128 v[182:185], v197
	ds_read_b128 v[186:189], v197 offset:1024
	ds_read_b128 v[200:203], v197 offset:2048
	ds_read_b128 v[204:207], v197 offset:3072
	ds_read_b128 v[208:211], v197 offset:4096
	ds_read_b128 v[212:215], v197 offset:5120
	ds_read_b128 v[218:221], v197 offset:6144
	ds_read_b128 v[222:225], v197 offset:7168
	global_load_lds_dwordx4 v178, s[72:73]
	s_add_i32 m0, s26, 0xe000
	s_nop 0
	global_load_lds_dwordx4 v180, s[72:73]
	s_waitcnt vmcnt(8)
	s_waitcnt lgkmcnt(0)
	s_barrier
	s_setprio 3
	s_waitcnt lgkmcnt(0)
	v_mfma_f32_16x16x128_f8f6f4 v[158:161], v[26:33], v[182:189], v[158:161]
	v_mfma_f32_16x16x128_f8f6f4 v[154:157], v[18:25], v[182:189], v[154:157]
	v_mfma_f32_16x16x128_f8f6f4 v[142:145], v[26:33], v[200:207], v[142:145]
	v_mfma_f32_16x16x128_f8f6f4 v[138:141], v[18:25], v[200:207], v[138:141]
	v_mfma_f32_16x16x128_f8f6f4 v[126:129], v[26:33], v[208:215], v[126:129]
	v_mfma_f32_16x16x128_f8f6f4 v[122:125], v[18:25], v[208:215], v[122:125]
	v_mfma_f32_16x16x128_f8f6f4 v[110:113], v[26:33], v[218:225], v[110:113]
	v_mfma_f32_16x16x128_f8f6f4 v[106:109], v[18:25], v[218:225], v[106:109]
	s_setprio 0
	s_setprio 3
	v_mfma_f32_16x16x128_f8f6f4 v[150:153], v[10:17], v[182:189], v[150:153]
	v_mfma_f32_16x16x128_f8f6f4 v[146:149], v[2:9], v[182:189], v[146:149]
	v_mfma_f32_16x16x128_f8f6f4 v[134:137], v[10:17], v[200:207], v[134:137]
	v_mfma_f32_16x16x128_f8f6f4 v[130:133], v[2:9], v[200:207], v[130:133]
	v_mfma_f32_16x16x128_f8f6f4 v[118:121], v[10:17], v[208:215], v[118:121]
	v_mfma_f32_16x16x128_f8f6f4 v[114:117], v[2:9], v[208:215], v[114:117]
	v_mfma_f32_16x16x128_f8f6f4 v[102:105], v[10:17], v[218:225], v[102:105]
	v_mfma_f32_16x16x128_f8f6f4 v[98:101], v[2:9], v[218:225], v[98:101]
	s_setprio 0
	s_add_i32 s24, s81, s14
	s_mov_b32 m0, s24
	ds_read_b128 v[200:203], v197 offset:16384
	ds_read_b128 v[204:207], v197 offset:17408
	ds_read_b128 v[208:211], v197 offset:18432
	ds_read_b128 v[212:215], v197 offset:19456
	ds_read_b128 v[218:221], v197 offset:20480
	ds_read_b128 v[222:225], v197 offset:21504
	ds_read_b128 v[226:229], v197 offset:22528
	ds_read_b128 v[230:233], v197 offset:23552
	global_load_lds_dwordx4 v166, s[74:75]
	s_add_i32 m0, s24, 0x2000
	s_add_u32 s24, s74, 0x40000
	s_addc_u32 s25, s75, 0
	s_add_i32 s36, s82, s14
	global_load_lds_dwordx4 v170, s[74:75]
	s_mov_b32 m0, s36
	s_nop 0
	global_load_lds_dwordx4 v166, s[24:25]
	s_add_i32 m0, s36, 0x2000
	s_nop 0
	global_load_lds_dwordx4 v170, s[24:25]
	s_mov_b32 m0, s26
	s_nop 0
	global_load_lds_dwordx4 v164, s[76:77]
	s_mov_b32 m0, s27
	s_nop 0
	global_load_lds_dwordx4 v168, s[76:77]
	s_waitcnt vmcnt(8)
	s_waitcnt lgkmcnt(0)
	s_barrier
; #define PG8_STAGE(bufoff, gbase, voff) do { _Pragma("unroll") for (int _i = 0; _i < 2; ++_i) \
;         __builtin_amdgcn_global_load_lds((const unsigned*)((const char*)(gbase) + (voff)[_i]), (PG8_LAS unsigned*)(lds + (bufoff) + ldsw + _i * 8192), 16, 0, 0); } while (0)
; #define PG8_LDA(dst, b, h) do { _Pragma("unroll") for (int m = 0; m < 4; ++m) _Pragma("unroll") for (int k = 0; k < 2; ++k) dst[m][k] = *(const PG8_LAS bf16x8*)(lds + PG8_SA(b, h) + aoff + m * 2048 + k * 1024); } while (0)
; #define PG8_LDB(dst, b, h) do { _Pragma("unroll") for (int n = 0; n < 2; ++n) _Pragma("unroll") for (int k = 0; k < 2; ++k) dst[n][k] = *(const PG8_LAS bf16x8*)(lds + PG8_SB(b, h) + boff + n * 2048 + k * 1024); } while (0)
; #define PG8_WAIT_V(n) asm volatile("s_waitcnt vmcnt(" #n ")" ::: "memory")
; #define PG8_WAIT_L(n) asm volatile("s_waitcnt lgkmcnt(" #n ")" ::: "memory")
; #define PG8_BAR __builtin_amdgcn_s_barrier()
; #define PG8_SCHED __builtin_amdgcn_sched_barrier(0)
; template <class Epi, class Sched, bool ALIGN_EPI = false, bool SP2 = false, bool F8 = false>
; __device__ __forceinline__ void gemm_phase(PG8_LAS unsigned char* lds, const Gemm g, const Sched& S, const Epi& E) {
;     ...
;             PG8_WAIT_V(8); PG8_WAIT_L(0); PG8_BAR; PG8_MMA(1, 0, At, B0); PG8_MMA(1, 1, At, B1); PG8_BAR; PG8_SCHED;
;             PG8_LDB(B0, 1, 0); PG8_LDB(B1, 1, 1); PG8_SCHED; PG8_LDA(At, 1, 0); PG8_STAGE(PG8_SA(0, 1), a2 + hstepA, voffA);
;             PG8_WAIT_V(8); PG8_WAIT_L(0); PG8_BAR; PG8_MMA(0, 0, At, B0); PG8_MMA(0, 1, At, B1); PG8_BAR; PG8_SCHED;
;             PG8_LDA(At, 1, 1); PG8_STAGE(PG8_SB(1, 0), b3, voffB); PG8_STAGE(PG8_SB(1, 1), b3 + hstep, voffB); PG8_STAGE(PG8_SA(1, 0), a3, voffA);
;             PG8_WAIT_V(8); PG8_WAIT_L(0); PG8_BAR; PG8_MMA(1, 0, At, B0); PG8_MMA(1, 1, At, B1); PG8_BAR; PG8_SCHED;
	s_setprio 3
	s_waitcnt lgkmcnt(0)
	v_mfma_f32_16x16x128_f8f6f4 v[94:97], v[26:33], v[200:207], v[94:97]
	v_mfma_f32_16x16x128_f8f6f4 v[90:93], v[18:25], v[200:207], v[90:93]
	v_mfma_f32_16x16x128_f8f6f4 v[78:81], v[26:33], v[208:215], v[78:81]
	v_mfma_f32_16x16x128_f8f6f4 v[74:77], v[18:25], v[208:215], v[74:77]
	v_mfma_f32_16x16x128_f8f6f4 v[62:65], v[26:33], v[218:225], v[62:65]
	v_mfma_f32_16x16x128_f8f6f4 v[58:61], v[18:25], v[218:225], v[58:61]
	v_mfma_f32_16x16x128_f8f6f4 v[46:49], v[26:33], v[226:233], v[46:49]
	v_mfma_f32_16x16x128_f8f6f4 v[42:45], v[18:25], v[226:233], v[42:45]
	s_setprio 0
	s_setprio 3
	v_mfma_f32_16x16x128_f8f6f4 v[86:89], v[10:17], v[200:207], v[86:89]
	v_mfma_f32_16x16x128_f8f6f4 v[82:85], v[2:9], v[200:207], v[82:85]
	v_mfma_f32_16x16x128_f8f6f4 v[70:73], v[10:17], v[208:215], v[70:73]
	v_mfma_f32_16x16x128_f8f6f4 v[66:69], v[2:9], v[208:215], v[66:69]
	v_mfma_f32_16x16x128_f8f6f4 v[54:57], v[10:17], v[218:225], v[54:57]
	v_mfma_f32_16x16x128_f8f6f4 v[50:53], v[2:9], v[218:225], v[50:53]
	v_mfma_f32_16x16x128_f8f6f4 v[38:41], v[10:17], v[226:233], v[38:41]
	v_mfma_f32_16x16x128_f8f6f4 v[34:37], v[2:9], v[226:233], v[34:37]
	s_setprio 0
	s_add_i32 s36, 0, 0x18000
	s_add_i32 s37, 0, 0x1c000
	v_add_u32_e32 v14, s36, v190
	v_add_u32_e32 v30, s37, v190
	ds_read_b128 v[2:5], v14
	ds_read_b128 v[6:9], v14 offset:1024
	ds_read_b128 v[10:13], v14 offset:2048
	ds_read_b128 v[14:17], v14 offset:3072
	ds_read_b128 v[18:21], v30
	ds_read_b128 v[22:25], v30 offset:1024
	ds_read_b128 v[26:29], v30 offset:2048
	ds_read_b128 v[30:33], v30 offset:3072
	s_add_u32 s24, s76, 0x40000
	s_addc_u32 s25, s77, 0
	s_mov_b32 m0, s28
	ds_read_b128 v[200:203], v197 offset:32768
	ds_read_b128 v[204:207], v197 offset:33792
	ds_read_b128 v[208:211], v197 offset:34816
	ds_read_b128 v[212:215], v197 offset:35840
	ds_read_b128 v[218:221], v197 offset:36864
	ds_read_b128 v[222:225], v197 offset:37888
	ds_read_b128 v[226:229], v197 offset:38912
	ds_read_b128 v[230:233], v197 offset:39936
	global_load_lds_dwordx4 v164, s[24:25]
	s_mov_b32 m0, s29
	s_nop 0
	global_load_lds_dwordx4 v168, s[24:25]
	s_waitcnt vmcnt(8)
	s_waitcnt lgkmcnt(0)
	s_barrier
	s_setprio 3
	s_waitcnt lgkmcnt(0)
	v_mfma_f32_16x16x128_f8f6f4 v[158:161], v[2:9], v[200:207], v[158:161]
	v_mfma_f32_16x16x128_f8f6f4 v[154:157], v[10:17], v[200:207], v[154:157]
	v_mfma_f32_16x16x128_f8f6f4 v[142:145], v[2:9], v[208:215], v[142:145]
	v_mfma_f32_16x16x128_f8f6f4 v[138:141], v[10:17], v[208:215], v[138:141]
	v_mfma_f32_16x16x128_f8f6f4 v[126:129], v[2:9], v[218:225], v[126:129]
	v_mfma_f32_16x16x128_f8f6f4 v[122:125], v[10:17], v[218:225], v[122:125]
	v_mfma_f32_16x16x128_f8f6f4 v[110:113], v[2:9], v[226:233], v[110:113]
	v_mfma_f32_16x16x128_f8f6f4 v[106:109], v[10:17], v[226:233], v[106:109]
	s_setprio 0
	s_setprio 3
	v_mfma_f32_16x16x128_f8f6f4 v[150:153], v[18:25], v[200:207], v[150:153]
	v_mfma_f32_16x16x128_f8f6f4 v[146:149], v[26:33], v[200:207], v[146:149]
	v_mfma_f32_16x16x128_f8f6f4 v[134:137], v[18:25], v[208:215], v[134:137]
	v_mfma_f32_16x16x128_f8f6f4 v[130:133], v[26:33], v[208:215], v[130:133]
	v_mfma_f32_16x16x128_f8f6f4 v[118:121], v[18:25], v[218:225], v[118:121]
	v_mfma_f32_16x16x128_f8f6f4 v[114:117], v[26:33], v[218:225], v[114:117]
	v_mfma_f32_16x16x128_f8f6f4 v[102:105], v[18:25], v[226:233], v[102:105]
	v_mfma_f32_16x16x128_f8f6f4 v[98:101], v[26:33], v[226:233], v[98:101]
	s_setprio 0
	s_add_i32 s24, s36, s14
	s_mov_b32 m0, s24
	ds_read_b128 v[200:203], v197 offset:49152
	ds_read_b128 v[204:207], v197 offset:50176
	ds_read_b128 v[208:211], v197 offset:51200
	ds_read_b128 v[212:215], v197 offset:52224
	ds_read_b128 v[218:221], v197 offset:53248
	ds_read_b128 v[222:225], v197 offset:54272
	ds_read_b128 v[226:229], v197 offset:55296
	ds_read_b128 v[230:233], v197 offset:56320
	s_add_u32 s98, s74, 0x80
	s_addc_u32 s99, s75, 0
	global_load_lds_dwordx4 v166, s[98:99]
	s_add_i32 m0, s24, 0x2000
	s_add_u32 s24, s74, 0x40080
	s_addc_u32 s25, s75, 0
	s_add_i32 s36, s37, s14
	s_add_u32 s100, s74, 0x80
	s_addc_u32 s101, s75, 0
	global_load_lds_dwordx4 v170, s[100:101]
	s_mov_b32 m0, s36
	s_nop 0
	global_load_lds_dwordx4 v166, s[24:25]
	s_add_i32 m0, s36, 0x2000
	s_nop 0
	global_load_lds_dwordx4 v170, s[24:25]
	s_mov_b32 m0, s45
	s_nop 0
	s_add_u32 s98, s76, 0x80
	s_addc_u32 s99, s77, 0
	global_load_lds_dwordx4 v164, s[98:99]
	s_mov_b32 m0, s78
	s_nop 0
	s_add_u32 s100, s76, 0x80
	s_addc_u32 s101, s77, 0
	global_load_lds_dwordx4 v168, s[100:101]
	s_waitcnt vmcnt(8)
	s_waitcnt lgkmcnt(0)
	s_barrier
	s_setprio 3
	s_waitcnt lgkmcnt(0)
	v_mfma_f32_16x16x128_f8f6f4 v[94:97], v[2:9], v[200:207], v[94:97]
	v_mfma_f32_16x16x128_f8f6f4 v[90:93], v[10:17], v[200:207], v[90:93]
	v_mfma_f32_16x16x128_f8f6f4 v[78:81], v[2:9], v[208:215], v[78:81]
	v_mfma_f32_16x16x128_f8f6f4 v[74:77], v[10:17], v[208:215], v[74:77]
	v_mfma_f32_16x16x128_f8f6f4 v[62:65], v[2:9], v[218:225], v[62:65]
	v_mfma_f32_16x16x128_f8f6f4 v[58:61], v[10:17], v[218:225], v[58:61]
	v_mfma_f32_16x16x128_f8f6f4 v[46:49], v[2:9], v[226:233], v[46:49]
	v_mfma_f32_16x16x128_f8f6f4 v[42:45], v[10:17], v[226:233], v[42:45]
	s_setprio 0
	s_setprio 3
	v_mfma_f32_16x16x128_f8f6f4 v[86:89], v[18:25], v[200:207], v[86:89]
	v_mfma_f32_16x16x128_f8f6f4 v[82:85], v[26:33], v[200:207], v[82:85]
	v_mfma_f32_16x16x128_f8f6f4 v[70:73], v[18:25], v[208:215], v[70:73]
	v_mfma_f32_16x16x128_f8f6f4 v[66:69], v[26:33], v[208:215], v[66:69]
	v_mfma_f32_16x16x128_f8f6f4 v[54:57], v[18:25], v[218:225], v[54:57]
	v_mfma_f32_16x16x128_f8f6f4 v[50:53], v[26:33], v[218:225], v[50:53]
	v_mfma_f32_16x16x128_f8f6f4 v[38:41], v[18:25], v[226:233], v[38:41]
	v_mfma_f32_16x16x128_f8f6f4 v[34:37], v[26:33], v[226:233], v[34:37]
	s_setprio 0
	s_add_i32 s87, s87, 2
	s_add_u32 s72, s72, 0x100
	s_addc_u32 s73, s73, 0
	s_add_u32 s85, s85, 0x100
	s_addc_u32 s86, s86, 0
	s_cmp_gt_u32 s87, 13
	s_cbranch_scc0 .Lk1_Y

; #define PG8_STAGE(bufoff, gbase, voff) do { _Pragma("unroll") for (int _i = 0; _i < 2; ++_i) \
;         __builtin_amdgcn_global_load_lds((const unsigned*)((const char*)(gbase) + (voff)[_i]), (PG8_LAS unsigned*)(lds + (bufoff) + ldsw + _i * 8192), 16, 0, 0); } while (0)
; #define PG8_LDA(dst, b, h) do { _Pragma("unroll") for (int m = 0; m < 4; ++m) _Pragma("unroll") for (int k = 0; k < 2; ++k) dst[m][k] = *(const PG8_LAS bf16x8*)(lds + PG8_SA(b, h) + aoff + m * 2048 + k * 1024); } while (0)
; #define PG8_WAIT_V(n) asm volatile("s_waitcnt vmcnt(" #n ")" ::: "memory")
; #define PG8_WAIT_L(n) asm volatile("s_waitcnt lgkmcnt(" #n ")" ::: "memory")
; #define PG8_BAR __builtin_amdgcn_s_barrier()
; template <class Epi, class Sched, bool ALIGN_EPI = false, bool SP2 = false, bool F8 = false>
; __device__ __forceinline__ void gemm_phase(PG8_LAS unsigned char* lds, const Gemm g, const Sched& S, const Epi& E) {
;     ...
;         for (int t = 0; t < nt; t += 2) {
;             const bool last = (t == nt - 2);
;             const char* a1 = cA + (size_t)(t + 1) * kstep;
;             const char* a2 = last ? nA : cA + (size_t)(t + 2) * kstep; const char* b2 = last ? nB : cB + (size_t)(t + 2) * kstep;
;             const char* a3 = a2 + kstep; const char* b3 = b2 + kstep;
;             if (last && has_next) S.a_ready(nxt);
;             if constexpr (SP2) {
;             PG8_LDB(B0, 0, 0); PG8_LDB(B1, 0, 1); PG8_SCHED; PG8_LDA(At, 0, 0); PG8_STAGE(PG8_SA(1, 1), a1 + hstepA, voffA);
;             PG8_WAIT_V(8); PG8_WAIT_L(0); PG8_BAR; PG8_MMA(0, 0, At, B0); PG8_MMA(0, 1, At, B1); PG8_BAR; PG8_SCHED;
;             PG8_LDA(At, 0, 1); PG8_STAGE(PG8_SB(0, 0), b2, voffB); PG8_STAGE(PG8_SB(0, 1), b2 + hstep, voffB); PG8_STAGE(PG8_SA(0, 0), a2, voffA);
;             PG8_WAIT_V(8); PG8_WAIT_L(0); PG8_BAR; PG8_MMA(1, 0, At, B0); PG8_MMA(1, 1, At, B1); PG8_BAR; PG8_SCHED;
;             PG8_LDB(B0, 1, 0); PG8_LDB(B1, 1, 1); PG8_SCHED; PG8_LDA(At, 1, 0); PG8_STAGE(PG8_SA(0, 1), a2 + hstepA, voffA);
;             PG8_WAIT_V(8); PG8_WAIT_L(0); PG8_BAR; PG8_MMA(0, 0, At, B0); PG8_MMA(0, 1, At, B1); PG8_BAR; PG8_SCHED;
;             PG8_LDA(At, 1, 1); PG8_STAGE(PG8_SB(1, 0), b3, voffB); PG8_STAGE(PG8_SB(1, 1), b3 + hstep, voffB); PG8_STAGE(PG8_SA(1, 0), a3, voffA);
;             PG8_WAIT_V(8); PG8_WAIT_L(0); PG8_BAR; PG8_MMA(1, 0, At, B0); PG8_MMA(1, 1, At, B1); PG8_BAR; PG8_SCHED;
.LBB0_772:
	ds_read_b128 v[82:85], v204
	ds_read_b128 v[86:89], v204 offset:1024
	ds_read_b128 v[90:93], v204 offset:2048
	ds_read_b128 v[94:97], v204 offset:3072
	ds_read_b128 v[102:105], v205
	ds_read_b128 v[106:109], v205 offset:1024
	ds_read_b128 v[114:117], v205 offset:2048
	ds_read_b128 v[118:121], v205 offset:3072
	s_add_u32 s24, s62, 0xfff80080
	s_addc_u32 s25, s63, -1
	s_cmp_eq_u32 s76, 28
	s_cselect_b32 s67, s55, s25
	s_cselect_b32 s66, s61, s24
	s_cselect_b32 s65, s53, s75
	s_cselect_b32 s64, s73, s74
	s_add_i32 m0, s15, 0xc000
	ds_read_b128 v[162:165], v206
	ds_read_b128 v[166:169], v206 offset:1024
	ds_read_b128 v[170:173], v206 offset:2048
	ds_read_b128 v[174:177], v206 offset:3072
	ds_read_b128 v[194:197], v206 offset:4096
	ds_read_b128 v[198:201], v206 offset:5120
	ds_read_b128 v[208:211], v206 offset:6144
	ds_read_b128 v[212:215], v206 offset:7168
	global_load_lds_dwordx4 v186, s[62:63]
	s_add_i32 m0, s15, 0xe000
	s_nop 0
	global_load_lds_dwordx4 v188, s[62:63]
	s_waitcnt vmcnt(8)
	s_waitcnt lgkmcnt(0)
	s_setprio 1
	s_waitcnt lgkmcnt(0)
	v_mfma_f32_16x16x32_bf16 v[158:161], v[82:85], v[162:165], v[158:161]
	v_mfma_f32_16x16x32_bf16 v[154:157], v[90:93], v[162:165], v[154:157]
	v_mfma_f32_16x16x32_bf16 v[142:145], v[82:85], v[170:173], v[142:145]
	v_mfma_f32_16x16x32_bf16 v[138:141], v[90:93], v[170:173], v[138:141]
	v_mfma_f32_16x16x32_bf16 v[126:129], v[82:85], v[194:197], v[126:129]
	v_mfma_f32_16x16x32_bf16 v[122:125], v[90:93], v[194:197], v[122:125]
	v_mfma_f32_16x16x32_bf16 v[78:81], v[82:85], v[208:211], v[78:81]
	v_mfma_f32_16x16x32_bf16 v[74:77], v[90:93], v[208:211], v[74:77]
	v_mfma_f32_16x16x32_bf16 v[158:161], v[86:89], v[166:169], v[158:161]
	v_mfma_f32_16x16x32_bf16 v[154:157], v[94:97], v[166:169], v[154:157]
	v_mfma_f32_16x16x32_bf16 v[142:145], v[86:89], v[174:177], v[142:145]
	v_mfma_f32_16x16x32_bf16 v[138:141], v[94:97], v[174:177], v[138:141]
	v_mfma_f32_16x16x32_bf16 v[126:129], v[86:89], v[198:201], v[126:129]
	v_mfma_f32_16x16x32_bf16 v[122:125], v[94:97], v[198:201], v[122:125]
	v_mfma_f32_16x16x32_bf16 v[78:81], v[86:89], v[212:215], v[78:81]
	v_mfma_f32_16x16x32_bf16 v[74:77], v[94:97], v[212:215], v[74:77]
	s_setprio 0
	s_setprio 1
	v_mfma_f32_16x16x32_bf16 v[150:153], v[102:105], v[162:165], v[150:153]
	v_mfma_f32_16x16x32_bf16 v[146:149], v[114:117], v[162:165], v[146:149]
	v_mfma_f32_16x16x32_bf16 v[134:137], v[102:105], v[170:173], v[134:137]
	v_mfma_f32_16x16x32_bf16 v[130:133], v[114:117], v[170:173], v[130:133]
	v_mfma_f32_16x16x32_bf16 v[110:113], v[102:105], v[194:197], v[110:113]
	v_mfma_f32_16x16x32_bf16 v[98:101], v[114:117], v[194:197], v[98:101]
	v_mfma_f32_16x16x32_bf16 v[70:73], v[102:105], v[208:211], v[70:73]
	v_mfma_f32_16x16x32_bf16 v[66:69], v[114:117], v[208:211], v[66:69]
	v_mfma_f32_16x16x32_bf16 v[150:153], v[106:109], v[166:169], v[150:153]
	v_mfma_f32_16x16x32_bf16 v[146:149], v[118:121], v[166:169], v[146:149]
	v_mfma_f32_16x16x32_bf16 v[134:137], v[106:109], v[174:177], v[134:137]
	v_mfma_f32_16x16x32_bf16 v[130:133], v[118:121], v[174:177], v[130:133]
	v_mfma_f32_16x16x32_bf16 v[110:113], v[106:109], v[198:201], v[110:113]
	v_mfma_f32_16x16x32_bf16 v[98:101], v[118:121], v[198:201], v[98:101]
	v_mfma_f32_16x16x32_bf16 v[70:73], v[106:109], v[212:215], v[70:73]
	v_mfma_f32_16x16x32_bf16 v[66:69], v[118:121], v[212:215], v[66:69]
	s_setprio 0
	s_barrier
	s_add_i32 s24, s70, s14
	s_mov_b32 m0, s24
	ds_read_b128 v[162:165], v206 offset:16384
	ds_read_b128 v[166:169], v206 offset:17408
	ds_read_b128 v[170:173], v206 offset:18432
	ds_read_b128 v[174:177], v206 offset:19456
	ds_read_b128 v[194:197], v206 offset:20480
	ds_read_b128 v[198:201], v206 offset:21504
	ds_read_b128 v[208:211], v206 offset:22528
	ds_read_b128 v[212:215], v206 offset:23552
	global_load_lds_dwordx4 v180, s[64:65]
	s_add_i32 m0, s24, 0x2000
	s_add_u32 s24, s64, 0x80000
	s_addc_u32 s25, s65, 0
	s_add_i32 s36, s71, s14
	global_load_lds_dwordx4 v184, s[64:65]
	s_mov_b32 m0, s36
	s_nop 0
	global_load_lds_dwordx4 v180, s[24:25]
	s_add_i32 m0, s36, 0x2000
	s_nop 0
	global_load_lds_dwordx4 v184, s[24:25]
	s_mov_b32 m0, s15
	s_nop 0
	global_load_lds_dwordx4 v178, s[66:67]
	s_mov_b32 m0, s23
	s_nop 0
	global_load_lds_dwordx4 v182, s[66:67]
	s_waitcnt vmcnt(8)
	s_waitcnt lgkmcnt(0)
	s_setprio 1
	s_waitcnt lgkmcnt(0)
	v_mfma_f32_16x16x32_bf16 v[62:65], v[82:85], v[162:165], v[62:65]
	v_mfma_f32_16x16x32_bf16 v[58:61], v[90:93], v[162:165], v[58:61]
	v_mfma_f32_16x16x32_bf16 v[46:49], v[82:85], v[170:173], v[46:49]
	v_mfma_f32_16x16x32_bf16 v[42:45], v[90:93], v[170:173], v[42:45]
	v_mfma_f32_16x16x32_bf16 v[30:33], v[82:85], v[194:197], v[30:33]
	v_mfma_f32_16x16x32_bf16 v[26:29], v[90:93], v[194:197], v[26:29]
	v_mfma_f32_16x16x32_bf16 v[14:17], v[82:85], v[208:211], v[14:17]
	v_mfma_f32_16x16x32_bf16 v[10:13], v[90:93], v[208:211], v[10:13]
	v_mfma_f32_16x16x32_bf16 v[62:65], v[86:89], v[166:169], v[62:65]
	v_mfma_f32_16x16x32_bf16 v[58:61], v[94:97], v[166:169], v[58:61]
	v_mfma_f32_16x16x32_bf16 v[46:49], v[86:89], v[174:177], v[46:49]
	v_mfma_f32_16x16x32_bf16 v[42:45], v[94:97], v[174:177], v[42:45]
	v_mfma_f32_16x16x32_bf16 v[30:33], v[86:89], v[198:201], v[30:33]
	v_mfma_f32_16x16x32_bf16 v[26:29], v[94:97], v[198:201], v[26:29]
	v_mfma_f32_16x16x32_bf16 v[14:17], v[86:89], v[212:215], v[14:17]
	v_mfma_f32_16x16x32_bf16 v[10:13], v[94:97], v[212:215], v[10:13]
	s_setprio 0
	s_setprio 1
	v_mfma_f32_16x16x32_bf16 v[54:57], v[102:105], v[162:165], v[54:57]
	v_mfma_f32_16x16x32_bf16 v[50:53], v[114:117], v[162:165], v[50:53]
	v_mfma_f32_16x16x32_bf16 v[38:41], v[102:105], v[170:173], v[38:41]
	v_mfma_f32_16x16x32_bf16 v[34:37], v[114:117], v[170:173], v[34:37]
	v_mfma_f32_16x16x32_bf16 v[22:25], v[102:105], v[194:197], v[22:25]
	v_mfma_f32_16x16x32_bf16 v[18:21], v[114:117], v[194:197], v[18:21]
	v_mfma_f32_16x16x32_bf16 v[6:9], v[102:105], v[208:211], v[6:9]
	v_mfma_f32_16x16x32_bf16 v[2:5], v[114:117], v[208:211], v[2:5]
	v_mfma_f32_16x16x32_bf16 v[54:57], v[106:109], v[166:169], v[54:57]
	v_mfma_f32_16x16x32_bf16 v[50:53], v[118:121], v[166:169], v[50:53]
	v_mfma_f32_16x16x32_bf16 v[38:41], v[106:109], v[174:177], v[38:41]
	v_mfma_f32_16x16x32_bf16 v[34:37], v[118:121], v[174:177], v[34:37]
	v_mfma_f32_16x16x32_bf16 v[22:25], v[106:109], v[198:201], v[22:25]
	v_mfma_f32_16x16x32_bf16 v[18:21], v[118:121], v[198:201], v[18:21]
	v_mfma_f32_16x16x32_bf16 v[6:9], v[106:109], v[212:215], v[6:9]
	v_mfma_f32_16x16x32_bf16 v[2:5], v[118:121], v[212:215], v[2:5]
	s_setprio 0
	s_barrier
; #define PG8_STAGE(bufoff, gbase, voff) do { _Pragma("unroll") for (int _i = 0; _i < 2; ++_i) \
;         __builtin_amdgcn_global_load_lds((const unsigned*)((const char*)(gbase) + (voff)[_i]), (PG8_LAS unsigned*)(lds + (bufoff) + ldsw + _i * 8192), 16, 0, 0); } while (0)
; #define PG8_LDA(dst, b, h) do { _Pragma("unroll") for (int m = 0; m < 4; ++m) _Pragma("unroll") for (int k = 0; k < 2; ++k) dst[m][k] = *(const PG8_LAS bf16x8*)(lds + PG8_SA(b, h) + aoff + m * 2048 + k * 1024); } while (0)
; #define PG8_WAIT_V(n) asm volatile("s_waitcnt vmcnt(" #n ")" ::: "memory")
; #define PG8_WAIT_L(n) asm volatile("s_waitcnt lgkmcnt(" #n ")" ::: "memory")
; #define PG8_BAR __builtin_amdgcn_s_barrier()
; template <class Epi, class Sched, bool ALIGN_EPI = false, bool SP2 = false, bool F8 = false>
; __device__ __forceinline__ void gemm_phase(PG8_LAS unsigned char* lds, const Gemm g, const Sched& S, const Epi& E) {
;     ...
;         for (int t = 0; t < nt; t += 2) {
;             const bool last = (t == nt - 2);
;             const char* a1 = cA + (size_t)(t + 1) * kstep;
;             const char* a2 = last ? nA : cA + (size_t)(t + 2) * kstep; const char* b2 = last ? nB : cB + (size_t)(t + 2) * kstep;
;             const char* a3 = a2 + kstep; const char* b3 = b2 + kstep;
;             if (last && has_next) S.a_ready(nxt);
;             if constexpr (SP2) {
;             PG8_LDB(B0, 0, 0); PG8_LDB(B1, 0, 1); PG8_SCHED; PG8_LDA(At, 0, 0); PG8_STAGE(PG8_SA(1, 1), a1 + hstepA, voffA);
;             PG8_WAIT_V(8); PG8_WAIT_L(0); PG8_BAR; PG8_MMA(0, 0, At, B0); PG8_MMA(0, 1, At, B1); PG8_BAR; PG8_SCHED;
;             PG8_LDA(At, 0, 1); PG8_STAGE(PG8_SB(0, 0), b2, voffB); PG8_STAGE(PG8_SB(0, 1), b2 + hstep, voffB); PG8_STAGE(PG8_SA(0, 0), a2, voffA);
;             PG8_WAIT_V(8); PG8_WAIT_L(0); PG8_BAR; PG8_MMA(1, 0, At, B0); PG8_MMA(1, 1, At, B1); PG8_BAR; PG8_SCHED;
;             PG8_LDB(B0, 1, 0); PG8_LDB(B1, 1, 1); PG8_SCHED; PG8_LDA(At, 1, 0); PG8_STAGE(PG8_SA(0, 1), a2 + hstepA, voffA);
;             PG8_WAIT_V(8); PG8_WAIT_L(0); PG8_BAR; PG8_MMA(0, 0, At, B0); PG8_MMA(0, 1, At, B1); PG8_BAR; PG8_SCHED;
;             PG8_LDA(At, 1, 1); PG8_STAGE(PG8_SB(1, 0), b3, voffB); PG8_STAGE(PG8_SB(1, 1), b3 + hstep, voffB); PG8_STAGE(PG8_SA(1, 0), a3, voffA);
;             PG8_WAIT_V(8); PG8_WAIT_L(0); PG8_BAR; PG8_MMA(1, 0, At, B0); PG8_MMA(1, 1, At, B1); PG8_BAR; PG8_SCHED;
	s_add_i32 s36, 0, 0x18000
	s_add_i32 s37, 0, 0x1c000
	v_add_u32_e32 v94, s36, v202
	v_add_u32_e32 v118, s37, v202
	ds_read_b128 v[82:85], v94
	ds_read_b128 v[86:89], v94 offset:1024
	ds_read_b128 v[90:93], v94 offset:2048
	ds_read_b128 v[94:97], v94 offset:3072
	ds_read_b128 v[102:105], v118
	ds_read_b128 v[106:109], v118 offset:1024
	ds_read_b128 v[114:117], v118 offset:2048
	ds_read_b128 v[118:121], v118 offset:3072
	s_add_u32 s24, s66, 0x80000
	s_addc_u32 s25, s67, 0
	s_mov_b32 m0, s26
	ds_read_b128 v[162:165], v206 offset:32768
	ds_read_b128 v[166:169], v206 offset:33792
	ds_read_b128 v[170:173], v206 offset:34816
	ds_read_b128 v[174:177], v206 offset:35840
	ds_read_b128 v[194:197], v206 offset:36864
	ds_read_b128 v[198:201], v206 offset:37888
	ds_read_b128 v[208:211], v206 offset:38912
	ds_read_b128 v[212:215], v206 offset:39936
	global_load_lds_dwordx4 v178, s[24:25]
	s_mov_b32 m0, s27
	s_nop 0
	global_load_lds_dwordx4 v182, s[24:25]
	s_waitcnt vmcnt(8)
	s_waitcnt lgkmcnt(0)
	s_setprio 1
	s_waitcnt lgkmcnt(0)
	v_mfma_f32_16x16x32_bf16 v[158:161], v[82:85], v[162:165], v[158:161]
	v_mfma_f32_16x16x32_bf16 v[154:157], v[90:93], v[162:165], v[154:157]
	v_mfma_f32_16x16x32_bf16 v[142:145], v[82:85], v[170:173], v[142:145]
	v_mfma_f32_16x16x32_bf16 v[138:141], v[90:93], v[170:173], v[138:141]
	v_mfma_f32_16x16x32_bf16 v[126:129], v[82:85], v[194:197], v[126:129]
	v_mfma_f32_16x16x32_bf16 v[122:125], v[90:93], v[194:197], v[122:125]
	v_mfma_f32_16x16x32_bf16 v[78:81], v[82:85], v[208:211], v[78:81]
	v_mfma_f32_16x16x32_bf16 v[74:77], v[90:93], v[208:211], v[74:77]
	v_mfma_f32_16x16x32_bf16 v[158:161], v[86:89], v[166:169], v[158:161]
	v_mfma_f32_16x16x32_bf16 v[154:157], v[94:97], v[166:169], v[154:157]
	v_mfma_f32_16x16x32_bf16 v[142:145], v[86:89], v[174:177], v[142:145]
	v_mfma_f32_16x16x32_bf16 v[138:141], v[94:97], v[174:177], v[138:141]
	v_mfma_f32_16x16x32_bf16 v[126:129], v[86:89], v[198:201], v[126:129]
	v_mfma_f32_16x16x32_bf16 v[122:125], v[94:97], v[198:201], v[122:125]
	v_mfma_f32_16x16x32_bf16 v[78:81], v[86:89], v[212:215], v[78:81]
	v_mfma_f32_16x16x32_bf16 v[74:77], v[94:97], v[212:215], v[74:77]
	s_setprio 0
	s_setprio 1
	v_mfma_f32_16x16x32_bf16 v[150:153], v[102:105], v[162:165], v[150:153]
	v_mfma_f32_16x16x32_bf16 v[146:149], v[114:117], v[162:165], v[146:149]
	v_mfma_f32_16x16x32_bf16 v[134:137], v[102:105], v[170:173], v[134:137]
	v_mfma_f32_16x16x32_bf16 v[130:133], v[114:117], v[170:173], v[130:133]
	v_mfma_f32_16x16x32_bf16 v[110:113], v[102:105], v[194:197], v[110:113]
	v_mfma_f32_16x16x32_bf16 v[98:101], v[114:117], v[194:197], v[98:101]
	v_mfma_f32_16x16x32_bf16 v[70:73], v[102:105], v[208:211], v[70:73]
	v_mfma_f32_16x16x32_bf16 v[66:69], v[114:117], v[208:211], v[66:69]
	v_mfma_f32_16x16x32_bf16 v[150:153], v[106:109], v[166:169], v[150:153]
	v_mfma_f32_16x16x32_bf16 v[146:149], v[118:121], v[166:169], v[146:149]
	v_mfma_f32_16x16x32_bf16 v[134:137], v[106:109], v[174:177], v[134:137]
	v_mfma_f32_16x16x32_bf16 v[130:133], v[118:121], v[174:177], v[130:133]
	v_mfma_f32_16x16x32_bf16 v[110:113], v[106:109], v[198:201], v[110:113]
	v_mfma_f32_16x16x32_bf16 v[98:101], v[118:121], v[198:201], v[98:101]
	v_mfma_f32_16x16x32_bf16 v[70:73], v[106:109], v[212:215], v[70:73]
	v_mfma_f32_16x16x32_bf16 v[66:69], v[118:121], v[212:215], v[66:69]
	s_setprio 0
	s_barrier
	s_add_i32 s24, s36, s14
	s_mov_b32 m0, s24
	ds_read_b128 v[162:165], v206 offset:49152
	ds_read_b128 v[166:169], v206 offset:50176
	ds_read_b128 v[170:173], v206 offset:51200
	ds_read_b128 v[174:177], v206 offset:52224
	ds_read_b128 v[194:197], v206 offset:53248
	ds_read_b128 v[198:201], v206 offset:54272
	ds_read_b128 v[208:211], v206 offset:55296
	ds_read_b128 v[212:215], v206 offset:56320
	s_add_u32 s98, s64, 0x80
	s_addc_u32 s99, s65, 0
	global_load_lds_dwordx4 v180, s[98:99]
	s_add_i32 m0, s24, 0x2000
	s_add_u32 s24, s64, 0x80080
	s_addc_u32 s25, s65, 0
	s_add_i32 s36, s37, s14
	s_add_u32 s100, s64, 0x80
	s_addc_u32 s101, s65, 0
	global_load_lds_dwordx4 v184, s[100:101]
	s_mov_b32 m0, s36
	s_nop 0
	global_load_lds_dwordx4 v180, s[24:25]
	s_add_i32 m0, s36, 0x2000
	s_nop 0
	global_load_lds_dwordx4 v184, s[24:25]
	s_mov_b32 m0, s44
	s_nop 0
	s_add_u32 s98, s66, 0x80
	s_addc_u32 s99, s67, 0
	global_load_lds_dwordx4 v178, s[98:99]
	s_mov_b32 m0, s45
	s_nop 0
	s_add_u32 s100, s66, 0x80
	s_addc_u32 s101, s67, 0
	global_load_lds_dwordx4 v182, s[100:101]
	s_waitcnt vmcnt(8)
	s_waitcnt lgkmcnt(0)
	s_setprio 1
	s_waitcnt lgkmcnt(0)
	v_mfma_f32_16x16x32_bf16 v[62:65], v[82:85], v[162:165], v[62:65]
	v_mfma_f32_16x16x32_bf16 v[58:61], v[90:93], v[162:165], v[58:61]
	v_mfma_f32_16x16x32_bf16 v[46:49], v[82:85], v[170:173], v[46:49]
	v_mfma_f32_16x16x32_bf16 v[42:45], v[90:93], v[170:173], v[42:45]
	v_mfma_f32_16x16x32_bf16 v[30:33], v[82:85], v[194:197], v[30:33]
	v_mfma_f32_16x16x32_bf16 v[26:29], v[90:93], v[194:197], v[26:29]
	v_mfma_f32_16x16x32_bf16 v[14:17], v[82:85], v[208:211], v[14:17]
	v_mfma_f32_16x16x32_bf16 v[10:13], v[90:93], v[208:211], v[10:13]
	v_mfma_f32_16x16x32_bf16 v[62:65], v[86:89], v[166:169], v[62:65]
	v_mfma_f32_16x16x32_bf16 v[58:61], v[94:97], v[166:169], v[58:61]
	v_mfma_f32_16x16x32_bf16 v[46:49], v[86:89], v[174:177], v[46:49]
	v_mfma_f32_16x16x32_bf16 v[42:45], v[94:97], v[174:177], v[42:45]
	v_mfma_f32_16x16x32_bf16 v[30:33], v[86:89], v[198:201], v[30:33]
	v_mfma_f32_16x16x32_bf16 v[26:29], v[94:97], v[198:201], v[26:29]
	v_mfma_f32_16x16x32_bf16 v[14:17], v[86:89], v[212:215], v[14:17]
	v_mfma_f32_16x16x32_bf16 v[10:13], v[94:97], v[212:215], v[10:13]
	s_setprio 0
	s_setprio 1
	v_mfma_f32_16x16x32_bf16 v[54:57], v[102:105], v[162:165], v[54:57]
	v_mfma_f32_16x16x32_bf16 v[50:53], v[114:117], v[162:165], v[50:53]
	v_mfma_f32_16x16x32_bf16 v[38:41], v[102:105], v[170:173], v[38:41]
	v_mfma_f32_16x16x32_bf16 v[34:37], v[114:117], v[170:173], v[34:37]
	v_mfma_f32_16x16x32_bf16 v[22:25], v[102:105], v[194:197], v[22:25]
	v_mfma_f32_16x16x32_bf16 v[18:21], v[114:117], v[194:197], v[18:21]
	v_mfma_f32_16x16x32_bf16 v[6:9], v[102:105], v[208:211], v[6:9]
	v_mfma_f32_16x16x32_bf16 v[2:5], v[114:117], v[208:211], v[2:5]
	v_mfma_f32_16x16x32_bf16 v[54:57], v[106:109], v[166:169], v[54:57]
	v_mfma_f32_16x16x32_bf16 v[50:53], v[118:121], v[166:169], v[50:53]
	v_mfma_f32_16x16x32_bf16 v[38:41], v[106:109], v[174:177], v[38:41]
	v_mfma_f32_16x16x32_bf16 v[34:37], v[118:121], v[174:177], v[34:37]
	v_mfma_f32_16x16x32_bf16 v[22:25], v[106:109], v[198:201], v[22:25]
	v_mfma_f32_16x16x32_bf16 v[18:21], v[118:121], v[198:201], v[18:21]
	v_mfma_f32_16x16x32_bf16 v[6:9], v[106:109], v[212:215], v[6:9]
	v_mfma_f32_16x16x32_bf16 v[2:5], v[118:121], v[212:215], v[2:5]
	s_setprio 0
	s_barrier
	s_add_i32 s76, s76, 2
	s_add_u32 s62, s62, 0x100
	s_addc_u32 s63, s63, 0
	s_add_u32 s74, s74, 0x100
	s_addc_u32 s75, s75, 0
	s_cmp_gt_u32 s76, 29
	s_cbranch_scc0 .LBB0_772
	s_branch .Lk2_exit
; #define PG8_STAGE(bufoff, gbase, voff) do { _Pragma("unroll") for (int _i = 0; _i < 2; ++_i) \
;         __builtin_amdgcn_global_load_lds((const unsigned*)((const char*)(gbase) + (voff)[_i]), (PG8_LAS unsigned*)(lds + (bufoff) + ldsw + _i * 8192), 16, 0, 0); } while (0)
; #define PG8_LDA(dst, b, h) do { _Pragma("unroll") for (int m = 0; m < 4; ++m) _Pragma("unroll") for (int k = 0; k < 2; ++k) dst[m][k] = *(const PG8_LAS bf16x8*)(lds + PG8_SA(b, h) + aoff + m * 2048 + k * 1024); } while (0)
; #define PG8_WAIT_V(n) asm volatile("s_waitcnt vmcnt(" #n ")" ::: "memory")
; #define PG8_WAIT_L(n) asm volatile("s_waitcnt lgkmcnt(" #n ")" ::: "memory")
; #define PG8_BAR __builtin_amdgcn_s_barrier()
; template <class Epi, class Sched, bool ALIGN_EPI = false, bool SP2 = false, bool F8 = false>
; __device__ __forceinline__ void gemm_phase(PG8_LAS unsigned char* lds, const Gemm g, const Sched& S, const Epi& E) {
;     ...
;         for (int t = 0; t < nt; t += 2) {
;             const bool last = (t == nt - 2);
;             const char* a1 = cA + (size_t)(t + 1) * kstep;
;             const char* a2 = last ? nA : cA + (size_t)(t + 2) * kstep; const char* b2 = last ? nB : cB + (size_t)(t + 2) * kstep;
;             const char* a3 = a2 + kstep; const char* b3 = b2 + kstep;
;             if (last && has_next) S.a_ready(nxt);
;             if constexpr (SP2) {
;             PG8_LDB(B0, 0, 0); PG8_LDB(B1, 0, 1); PG8_SCHED; PG8_LDA(At, 0, 0); PG8_STAGE(PG8_SA(1, 1), a1 + hstepA, voffA);
;             PG8_WAIT_V(8); PG8_WAIT_L(0); PG8_BAR; PG8_MMA(0, 0, At, B0); PG8_MMA(0, 1, At, B1); PG8_BAR; PG8_SCHED;
;             PG8_LDA(At, 0, 1); PG8_STAGE(PG8_SB(0, 0), b2, voffB); PG8_STAGE(PG8_SB(0, 1), b2 + hstep, voffB); PG8_STAGE(PG8_SA(0, 0), a2, voffA);
;             PG8_WAIT_V(8); PG8_WAIT_L(0); PG8_BAR; PG8_MMA(1, 0, At, B0); PG8_MMA(1, 1, At, B1); PG8_BAR; PG8_SCHED;
;             PG8_LDB(B0, 1, 0); PG8_LDB(B1, 1, 1); PG8_SCHED; PG8_LDA(At, 1, 0); PG8_STAGE(PG8_SA(0, 1), a2 + hstepA, voffA);
;             PG8_WAIT_V(8); PG8_WAIT_L(0); PG8_BAR; PG8_MMA(0, 0, At, B0); PG8_MMA(0, 1, At, B1); PG8_BAR; PG8_SCHED;
;             PG8_LDA(At, 1, 1); PG8_STAGE(PG8_SB(1, 0), b3, voffB); PG8_STAGE(PG8_SB(1, 1), b3 + hstep, voffB); PG8_STAGE(PG8_SA(1, 0), a3, voffA);
;             PG8_WAIT_V(8); PG8_WAIT_L(0); PG8_BAR; PG8_MMA(1, 0, At, B0); PG8_MMA(1, 1, At, B1); PG8_BAR; PG8_SCHED;
.Lk2_Y:
	ds_read_b128 v[82:85], v204
	ds_read_b128 v[86:89], v204 offset:1024
	ds_read_b128 v[90:93], v204 offset:2048
	ds_read_b128 v[94:97], v204 offset:3072
	ds_read_b128 v[102:105], v205
	ds_read_b128 v[106:109], v205 offset:1024
	ds_read_b128 v[114:117], v205 offset:2048
	ds_read_b128 v[118:121], v205 offset:3072
	s_add_u32 s24, s62, 0xfff80080
	s_addc_u32 s25, s63, -1
	s_cmp_eq_u32 s76, 28
	s_cselect_b32 s67, s55, s25
	s_cselect_b32 s66, s61, s24
	s_cselect_b32 s65, s53, s75
	s_cselect_b32 s64, s73, s74
	s_add_i32 m0, s15, 0xc000
	ds_read_b128 v[162:165], v206
	ds_read_b128 v[166:169], v206 offset:1024
	ds_read_b128 v[170:173], v206 offset:2048
	ds_read_b128 v[174:177], v206 offset:3072
	ds_read_b128 v[194:197], v206 offset:4096
	ds_read_b128 v[198:201], v206 offset:5120
	ds_read_b128 v[208:211], v206 offset:6144
	ds_read_b128 v[212:215], v206 offset:7168
	global_load_lds_dwordx4 v186, s[62:63]
	s_add_i32 m0, s15, 0xe000
	s_nop 0
	global_load_lds_dwordx4 v188, s[62:63]
	s_waitcnt vmcnt(8)
	s_waitcnt lgkmcnt(0)
	s_barrier
	s_setprio 3
	s_waitcnt lgkmcnt(0)
	v_mfma_f32_16x16x32_bf16 v[158:161], v[82:85], v[162:165], v[158:161]
	v_mfma_f32_16x16x32_bf16 v[154:157], v[90:93], v[162:165], v[154:157]
	v_mfma_f32_16x16x32_bf16 v[142:145], v[82:85], v[170:173], v[142:145]
	v_mfma_f32_16x16x32_bf16 v[138:141], v[90:93], v[170:173], v[138:141]
	v_mfma_f32_16x16x32_bf16 v[126:129], v[82:85], v[194:197], v[126:129]
	v_mfma_f32_16x16x32_bf16 v[122:125], v[90:93], v[194:197], v[122:125]
	v_mfma_f32_16x16x32_bf16 v[78:81], v[82:85], v[208:211], v[78:81]
	v_mfma_f32_16x16x32_bf16 v[74:77], v[90:93], v[208:211], v[74:77]
	v_mfma_f32_16x16x32_bf16 v[158:161], v[86:89], v[166:169], v[158:161]
	v_mfma_f32_16x16x32_bf16 v[154:157], v[94:97], v[166:169], v[154:157]
	v_mfma_f32_16x16x32_bf16 v[142:145], v[86:89], v[174:177], v[142:145]
	v_mfma_f32_16x16x32_bf16 v[138:141], v[94:97], v[174:177], v[138:141]
	v_mfma_f32_16x16x32_bf16 v[126:129], v[86:89], v[198:201], v[126:129]
	v_mfma_f32_16x16x32_bf16 v[122:125], v[94:97], v[198:201], v[122:125]
	v_mfma_f32_16x16x32_bf16 v[78:81], v[86:89], v[212:215], v[78:81]
	v_mfma_f32_16x16x32_bf16 v[74:77], v[94:97], v[212:215], v[74:77]
	s_setprio 0
	s_setprio 3
	v_mfma_f32_16x16x32_bf16 v[150:153], v[102:105], v[162:165], v[150:153]
	v_mfma_f32_16x16x32_bf16 v[146:149], v[114:117], v[162:165], v[146:149]
	v_mfma_f32_16x16x32_bf16 v[134:137], v[102:105], v[170:173], v[134:137]
	v_mfma_f32_16x16x32_bf16 v[130:133], v[114:117], v[170:173], v[130:133]
	v_mfma_f32_16x16x32_bf16 v[110:113], v[102:105], v[194:197], v[110:113]
	v_mfma_f32_16x16x32_bf16 v[98:101], v[114:117], v[194:197], v[98:101]
	v_mfma_f32_16x16x32_bf16 v[70:73], v[102:105], v[208:211], v[70:73]
	v_mfma_f32_16x16x32_bf16 v[66:69], v[114:117], v[208:211], v[66:69]
	v_mfma_f32_16x16x32_bf16 v[150:153], v[106:109], v[166:169], v[150:153]
	v_mfma_f32_16x16x32_bf16 v[146:149], v[118:121], v[166:169], v[146:149]
	v_mfma_f32_16x16x32_bf16 v[134:137], v[106:109], v[174:177], v[134:137]
	v_mfma_f32_16x16x32_bf16 v[130:133], v[118:121], v[174:177], v[130:133]
	v_mfma_f32_16x16x32_bf16 v[110:113], v[106:109], v[198:201], v[110:113]
	v_mfma_f32_16x16x32_bf16 v[98:101], v[118:121], v[198:201], v[98:101]
	v_mfma_f32_16x16x32_bf16 v[70:73], v[106:109], v[212:215], v[70:73]
	v_mfma_f32_16x16x32_bf16 v[66:69], v[118:121], v[212:215], v[66:69]
	s_setprio 0
	s_add_i32 s24, s70, s14
	s_mov_b32 m0, s24
	ds_read_b128 v[162:165], v206 offset:16384
	ds_read_b128 v[166:169], v206 offset:17408
	ds_read_b128 v[170:173], v206 offset:18432
	ds_read_b128 v[174:177], v206 offset:19456
	ds_read_b128 v[194:197], v206 offset:20480
	ds_read_b128 v[198:201], v206 offset:21504
	ds_read_b128 v[208:211], v206 offset:22528
	ds_read_b128 v[212:215], v206 offset:23552
	global_load_lds_dwordx4 v180, s[64:65]
	s_add_i32 m0, s24, 0x2000
	s_add_u32 s24, s64, 0x80000
	s_addc_u32 s25, s65, 0
	s_add_i32 s36, s71, s14
	global_load_lds_dwordx4 v184, s[64:65]
	s_mov_b32 m0, s36
	s_nop 0
	global_load_lds_dwordx4 v180, s[24:25]
	s_add_i32 m0, s36, 0x2000
	s_nop 0
	global_load_lds_dwordx4 v184, s[24:25]
	s_mov_b32 m0, s15
	s_nop 0
	global_load_lds_dwordx4 v178, s[66:67]
	s_mov_b32 m0, s23
	s_nop 0
	global_load_lds_dwordx4 v182, s[66:67]
	s_waitcnt vmcnt(8)
	s_waitcnt lgkmcnt(0)
	s_barrier
; #define PG8_STAGE(bufoff, gbase, voff) do { _Pragma("unroll") for (int _i = 0; _i < 2; ++_i) \
;         __builtin_amdgcn_global_load_lds((const unsigned*)((const char*)(gbase) + (voff)[_i]), (PG8_LAS unsigned*)(lds + (bufoff) + ldsw + _i * 8192), 16, 0, 0); } while (0)
; #define PG8_LDA(dst, b, h) do { _Pragma("unroll") for (int m = 0; m < 4; ++m) _Pragma("unroll") for (int k = 0; k < 2; ++k) dst[m][k] = *(const PG8_LAS bf16x8*)(lds + PG8_SA(b, h) + aoff + m * 2048 + k * 1024); } while (0)
; #define PG8_LDB(dst, b, h) do { _Pragma("unroll") for (int n = 0; n < 2; ++n) _Pragma("unroll") for (int k = 0; k < 2; ++k) dst[n][k] = *(const PG8_LAS bf16x8*)(lds + PG8_SB(b, h) + boff + n * 2048 + k * 1024); } while (0)
; #define PG8_WAIT_V(n) asm volatile("s_waitcnt vmcnt(" #n ")" ::: "memory")
; #define PG8_WAIT_L(n) asm volatile("s_waitcnt lgkmcnt(" #n ")" ::: "memory")
; #define PG8_BAR __builtin_amdgcn_s_barrier()
; #define PG8_SCHED __builtin_amdgcn_sched_barrier(0)
; template <class Epi, class Sched, bool ALIGN_EPI = false, bool SP2 = false, bool F8 = false>
; __device__ __forceinline__ void gemm_phase(PG8_LAS unsigned char* lds, const Gemm g, const Sched& S, const Epi& E) {
;     ...
;             PG8_LDB(B0, 0, 0); PG8_LDB(B1, 0, 1); PG8_SCHED; PG8_LDA(At, 0, 0); PG8_STAGE(PG8_SA(1, 1), a1 + hstepA, voffA);
;             PG8_WAIT_V(8); PG8_WAIT_L(0); PG8_BAR; PG8_MMA(0, 0, At, B0); PG8_MMA(0, 1, At, B1); PG8_BAR; PG8_SCHED;
;             PG8_LDA(At, 0, 1); PG8_STAGE(PG8_SB(0, 0), b2, voffB); PG8_STAGE(PG8_SB(0, 1), b2 + hstep, voffB); PG8_STAGE(PG8_SA(0, 0), a2, voffA);
;             PG8_WAIT_V(8); PG8_WAIT_L(0); PG8_BAR; PG8_MMA(1, 0, At, B0); PG8_MMA(1, 1, At, B1); PG8_BAR; PG8_SCHED;
	s_setprio 3
	s_waitcnt lgkmcnt(0)
	v_mfma_f32_16x16x32_bf16 v[62:65], v[82:85], v[162:165], v[62:65]
	v_mfma_f32_16x16x32_bf16 v[58:61], v[90:93], v[162:165], v[58:61]
	v_mfma_f32_16x16x32_bf16 v[46:49], v[82:85], v[170:173], v[46:49]
	v_mfma_f32_16x16x32_bf16 v[42:45], v[90:93], v[170:173], v[42:45]
	v_mfma_f32_16x16x32_bf16 v[30:33], v[82:85], v[194:197], v[30:33]
	v_mfma_f32_16x16x32_bf16 v[26:29], v[90:93], v[194:197], v[26:29]
	v_mfma_f32_16x16x32_bf16 v[14:17], v[82:85], v[208:211], v[14:17]
	v_mfma_f32_16x16x32_bf16 v[10:13], v[90:93], v[208:211], v[10:13]
	v_mfma_f32_16x16x32_bf16 v[62:65], v[86:89], v[166:169], v[62:65]
	v_mfma_f32_16x16x32_bf16 v[58:61], v[94:97], v[166:169], v[58:61]
	v_mfma_f32_16x16x32_bf16 v[46:49], v[86:89], v[174:177], v[46:49]
	v_mfma_f32_16x16x32_bf16 v[42:45], v[94:97], v[174:177], v[42:45]
	v_mfma_f32_16x16x32_bf16 v[30:33], v[86:89], v[198:201], v[30:33]
	v_mfma_f32_16x16x32_bf16 v[26:29], v[94:97], v[198:201], v[26:29]
	v_mfma_f32_16x16x32_bf16 v[14:17], v[86:89], v[212:215], v[14:17]
	v_mfma_f32_16x16x32_bf16 v[10:13], v[94:97], v[212:215], v[10:13]
	s_setprio 0
	s_setprio 3
	v_mfma_f32_16x16x32_bf16 v[54:57], v[102:105], v[162:165], v[54:57]
	v_mfma_f32_16x16x32_bf16 v[50:53], v[114:117], v[162:165], v[50:53]
	v_mfma_f32_16x16x32_bf16 v[38:41], v[102:105], v[170:173], v[38:41]
	v_mfma_f32_16x16x32_bf16 v[34:37], v[114:117], v[170:173], v[34:37]
	v_mfma_f32_16x16x32_bf16 v[22:25], v[102:105], v[194:197], v[22:25]
	v_mfma_f32_16x16x32_bf16 v[18:21], v[114:117], v[194:197], v[18:21]
	v_mfma_f32_16x16x32_bf16 v[6:9], v[102:105], v[208:211], v[6:9]
	v_mfma_f32_16x16x32_bf16 v[2:5], v[114:117], v[208:211], v[2:5]
	v_mfma_f32_16x16x32_bf16 v[54:57], v[106:109], v[166:169], v[54:57]
	v_mfma_f32_16x16x32_bf16 v[50:53], v[118:121], v[166:169], v[50:53]
	v_mfma_f32_16x16x32_bf16 v[38:41], v[106:109], v[174:177], v[38:41]
	v_mfma_f32_16x16x32_bf16 v[34:37], v[118:121], v[174:177], v[34:37]
	v_mfma_f32_16x16x32_bf16 v[22:25], v[106:109], v[198:201], v[22:25]
	v_mfma_f32_16x16x32_bf16 v[18:21], v[118:121], v[198:201], v[18:21]
	v_mfma_f32_16x16x32_bf16 v[6:9], v[106:109], v[212:215], v[6:9]
	v_mfma_f32_16x16x32_bf16 v[2:5], v[118:121], v[212:215], v[2:5]
	s_setprio 0
	s_add_i32 s36, 0, 0x18000
	s_add_i32 s37, 0, 0x1c000
	v_add_u32_e32 v94, s36, v202
	v_add_u32_e32 v118, s37, v202
	ds_read_b128 v[82:85], v94
	ds_read_b128 v[86:89], v94 offset:1024
	ds_read_b128 v[90:93], v94 offset:2048
	ds_read_b128 v[94:97], v94 offset:3072
	ds_read_b128 v[102:105], v118
	ds_read_b128 v[106:109], v118 offset:1024
	ds_read_b128 v[114:117], v118 offset:2048
	ds_read_b128 v[118:121], v118 offset:3072
	s_add_u32 s24, s66, 0x80000
	s_addc_u32 s25, s67, 0
	s_mov_b32 m0, s26
	ds_read_b128 v[162:165], v206 offset:32768
	ds_read_b128 v[166:169], v206 offset:33792
	ds_read_b128 v[170:173], v206 offset:34816
	ds_read_b128 v[174:177], v206 offset:35840
	ds_read_b128 v[194:197], v206 offset:36864
	ds_read_b128 v[198:201], v206 offset:37888
	ds_read_b128 v[208:211], v206 offset:38912
	ds_read_b128 v[212:215], v206 offset:39936
	global_load_lds_dwordx4 v178, s[24:25]
	s_mov_b32 m0, s27
	s_nop 0
	global_load_lds_dwordx4 v182, s[24:25]
	s_waitcnt vmcnt(8)
	s_waitcnt lgkmcnt(0)
	s_barrier
; #define PG8_STAGE(bufoff, gbase, voff) do { _Pragma("unroll") for (int _i = 0; _i < 2; ++_i) \
;         __builtin_amdgcn_global_load_lds((const unsigned*)((const char*)(gbase) + (voff)[_i]), (PG8_LAS unsigned*)(lds + (bufoff) + ldsw + _i * 8192), 16, 0, 0); } while (0)
; #define PG8_LDA(dst, b, h) do { _Pragma("unroll") for (int m = 0; m < 4; ++m) _Pragma("unroll") for (int k = 0; k < 2; ++k) dst[m][k] = *(const PG8_LAS bf16x8*)(lds + PG8_SA(b, h) + aoff + m * 2048 + k * 1024); } while (0)
; #define PG8_LDB(dst, b, h) do { _Pragma("unroll") for (int n = 0; n < 2; ++n) _Pragma("unroll") for (int k = 0; k < 2; ++k) dst[n][k] = *(const PG8_LAS bf16x8*)(lds + PG8_SB(b, h) + boff + n * 2048 + k * 1024); } while (0)
; #define PG8_WAIT_V(n) asm volatile("s_waitcnt vmcnt(" #n ")" ::: "memory")
; #define PG8_WAIT_L(n) asm volatile("s_waitcnt lgkmcnt(" #n ")" ::: "memory")
; #define PG8_BAR __builtin_amdgcn_s_barrier()
; #define PG8_SCHED __builtin_amdgcn_sched_barrier(0)
; template <class Epi, class Sched, bool ALIGN_EPI = false, bool SP2 = false, bool F8 = false>
; __device__ __forceinline__ void gemm_phase(PG8_LAS unsigned char* lds, const Gemm g, const Sched& S, const Epi& E) {
;     ...
;             PG8_LDB(B0, 1, 0); PG8_LDB(B1, 1, 1); PG8_SCHED; PG8_LDA(At, 1, 0); PG8_STAGE(PG8_SA(0, 1), a2 + hstepA, voffA);
;             PG8_WAIT_V(8); PG8_WAIT_L(0); PG8_BAR; PG8_MMA(0, 0, At, B0); PG8_MMA(0, 1, At, B1); PG8_BAR; PG8_SCHED;
;             PG8_LDA(At, 1, 1); PG8_STAGE(PG8_SB(1, 0), b3, voffB); PG8_STAGE(PG8_SB(1, 1), b3 + hstep, voffB); PG8_STAGE(PG8_SA(1, 0), a3, voffA);
;             PG8_WAIT_V(8); PG8_WAIT_L(0); PG8_BAR; PG8_MMA(1, 0, At, B0); PG8_MMA(1, 1, At, B1); PG8_BAR; PG8_SCHED;
	s_setprio 3
	s_waitcnt lgkmcnt(0)
	v_mfma_f32_16x16x32_bf16 v[158:161], v[82:85], v[162:165], v[158:161]
	v_mfma_f32_16x16x32_bf16 v[154:157], v[90:93], v[162:165], v[154:157]
	v_mfma_f32_16x16x32_bf16 v[142:145], v[82:85], v[170:173], v[142:145]
	v_mfma_f32_16x16x32_bf16 v[138:141], v[90:93], v[170:173], v[138:141]
	v_mfma_f32_16x16x32_bf16 v[126:129], v[82:85], v[194:197], v[126:129]
	v_mfma_f32_16x16x32_bf16 v[122:125], v[90:93], v[194:197], v[122:125]
	v_mfma_f32_16x16x32_bf16 v[78:81], v[82:85], v[208:211], v[78:81]
	v_mfma_f32_16x16x32_bf16 v[74:77], v[90:93], v[208:211], v[74:77]
	v_mfma_f32_16x16x32_bf16 v[158:161], v[86:89], v[166:169], v[158:161]
	v_mfma_f32_16x16x32_bf16 v[154:157], v[94:97], v[166:169], v[154:157]
	v_mfma_f32_16x16x32_bf16 v[142:145], v[86:89], v[174:177], v[142:145]
	v_mfma_f32_16x16x32_bf16 v[138:141], v[94:97], v[174:177], v[138:141]
	v_mfma_f32_16x16x32_bf16 v[126:129], v[86:89], v[198:201], v[126:129]
	v_mfma_f32_16x16x32_bf16 v[122:125], v[94:97], v[198:201], v[122:125]
	v_mfma_f32_16x16x32_bf16 v[78:81], v[86:89], v[212:215], v[78:81]
	v_mfma_f32_16x16x32_bf16 v[74:77], v[94:97], v[212:215], v[74:77]
	s_setprio 0
	s_setprio 3
	v_mfma_f32_16x16x32_bf16 v[150:153], v[102:105], v[162:165], v[150:153]
	v_mfma_f32_16x16x32_bf16 v[146:149], v[114:117], v[162:165], v[146:149]
	v_mfma_f32_16x16x32_bf16 v[134:137], v[102:105], v[170:173], v[134:137]
	v_mfma_f32_16x16x32_bf16 v[130:133], v[114:117], v[170:173], v[130:133]
	v_mfma_f32_16x16x32_bf16 v[110:113], v[102:105], v[194:197], v[110:113]
	v_mfma_f32_16x16x32_bf16 v[98:101], v[114:117], v[194:197], v[98:101]
	v_mfma_f32_16x16x32_bf16 v[70:73], v[102:105], v[208:211], v[70:73]
	v_mfma_f32_16x16x32_bf16 v[66:69], v[114:117], v[208:211], v[66:69]
	v_mfma_f32_16x16x32_bf16 v[150:153], v[106:109], v[166:169], v[150:153]
	v_mfma_f32_16x16x32_bf16 v[146:149], v[118:121], v[166:169], v[146:149]
	v_mfma_f32_16x16x32_bf16 v[134:137], v[106:109], v[174:177], v[134:137]
	v_mfma_f32_16x16x32_bf16 v[130:133], v[118:121], v[174:177], v[130:133]
	v_mfma_f32_16x16x32_bf16 v[110:113], v[106:109], v[198:201], v[110:113]
	v_mfma_f32_16x16x32_bf16 v[98:101], v[118:121], v[198:201], v[98:101]
	v_mfma_f32_16x16x32_bf16 v[70:73], v[106:109], v[212:215], v[70:73]
	v_mfma_f32_16x16x32_bf16 v[66:69], v[118:121], v[212:215], v[66:69]
	s_setprio 0
	s_add_i32 s24, s36, s14
	s_mov_b32 m0, s24
	ds_read_b128 v[162:165], v206 offset:49152
	ds_read_b128 v[166:169], v206 offset:50176
	ds_read_b128 v[170:173], v206 offset:51200
	ds_read_b128 v[174:177], v206 offset:52224
	ds_read_b128 v[194:197], v206 offset:53248
	ds_read_b128 v[198:201], v206 offset:54272
	ds_read_b128 v[208:211], v206 offset:55296
	ds_read_b128 v[212:215], v206 offset:56320
	s_add_u32 s98, s64, 0x80
	s_addc_u32 s99, s65, 0
	global_load_lds_dwordx4 v180, s[98:99]
	s_add_i32 m0, s24, 0x2000
	s_add_u32 s24, s64, 0x80080
	s_addc_u32 s25, s65, 0
	s_add_i32 s36, s37, s14
	s_add_u32 s100, s64, 0x80
	s_addc_u32 s101, s65, 0
	global_load_lds_dwordx4 v184, s[100:101]
	s_mov_b32 m0, s36
	s_nop 0
	global_load_lds_dwordx4 v180, s[24:25]
	s_add_i32 m0, s36, 0x2000
	s_nop 0
	global_load_lds_dwordx4 v184, s[24:25]
	s_mov_b32 m0, s44
	s_nop 0
	s_add_u32 s98, s66, 0x80
	s_addc_u32 s99, s67, 0
	global_load_lds_dwordx4 v178, s[98:99]
	s_mov_b32 m0, s45
	s_nop 0
	s_add_u32 s100, s66, 0x80
	s_addc_u32 s101, s67, 0
	global_load_lds_dwordx4 v182, s[100:101]
	s_waitcnt vmcnt(8)
	s_waitcnt lgkmcnt(0)
	s_barrier
	s_setprio 3
	s_waitcnt lgkmcnt(0)
	v_mfma_f32_16x16x32_bf16 v[62:65], v[82:85], v[162:165], v[62:65]
	v_mfma_f32_16x16x32_bf16 v[58:61], v[90:93], v[162:165], v[58:61]
	v_mfma_f32_16x16x32_bf16 v[46:49], v[82:85], v[170:173], v[46:49]
	v_mfma_f32_16x16x32_bf16 v[42:45], v[90:93], v[170:173], v[42:45]
	v_mfma_f32_16x16x32_bf16 v[30:33], v[82:85], v[194:197], v[30:33]
	v_mfma_f32_16x16x32_bf16 v[26:29], v[90:93], v[194:197], v[26:29]
	v_mfma_f32_16x16x32_bf16 v[14:17], v[82:85], v[208:211], v[14:17]
	v_mfma_f32_16x16x32_bf16 v[10:13], v[90:93], v[208:211], v[10:13]
	v_mfma_f32_16x16x32_bf16 v[62:65], v[86:89], v[166:169], v[62:65]
	v_mfma_f32_16x16x32_bf16 v[58:61], v[94:97], v[166:169], v[58:61]
	v_mfma_f32_16x16x32_bf16 v[46:49], v[86:89], v[174:177], v[46:49]
	v_mfma_f32_16x16x32_bf16 v[42:45], v[94:97], v[174:177], v[42:45]
	v_mfma_f32_16x16x32_bf16 v[30:33], v[86:89], v[198:201], v[30:33]
	v_mfma_f32_16x16x32_bf16 v[26:29], v[94:97], v[198:201], v[26:29]
	v_mfma_f32_16x16x32_bf16 v[14:17], v[86:89], v[212:215], v[14:17]
	v_mfma_f32_16x16x32_bf16 v[10:13], v[94:97], v[212:215], v[10:13]
	s_setprio 0
	s_setprio 3
	v_mfma_f32_16x16x32_bf16 v[54:57], v[102:105], v[162:165], v[54:57]
	v_mfma_f32_16x16x32_bf16 v[50:53], v[114:117], v[162:165], v[50:53]
	v_mfma_f32_16x16x32_bf16 v[38:41], v[102:105], v[170:173], v[38:41]
	v_mfma_f32_16x16x32_bf16 v[34:37], v[114:117], v[170:173], v[34:37]
	v_mfma_f32_16x16x32_bf16 v[22:25], v[102:105], v[194:197], v[22:25]
	v_mfma_f32_16x16x32_bf16 v[18:21], v[114:117], v[194:197], v[18:21]
	v_mfma_f32_16x16x32_bf16 v[6:9], v[102:105], v[208:211], v[6:9]
	v_mfma_f32_16x16x32_bf16 v[2:5], v[114:117], v[208:211], v[2:5]
	v_mfma_f32_16x16x32_bf16 v[54:57], v[106:109], v[166:169], v[54:57]
	v_mfma_f32_16x16x32_bf16 v[50:53], v[118:121], v[166:169], v[50:53]
	v_mfma_f32_16x16x32_bf16 v[38:41], v[106:109], v[174:177], v[38:41]
	v_mfma_f32_16x16x32_bf16 v[34:37], v[118:121], v[174:177], v[34:37]
	v_mfma_f32_16x16x32_bf16 v[22:25], v[106:109], v[198:201], v[22:25]
	v_mfma_f32_16x16x32_bf16 v[18:21], v[118:121], v[198:201], v[18:21]
	v_mfma_f32_16x16x32_bf16 v[6:9], v[106:109], v[212:215], v[6:9]
	v_mfma_f32_16x16x32_bf16 v[2:5], v[118:121], v[212:215], v[2:5]
	s_setprio 0
	s_add_i32 s76, s76, 2
	s_add_u32 s62, s62, 0x100
	s_addc_u32 s63, s63, 0
	s_add_u32 s74, s74, 0x100
	s_addc_u32 s75, s75, 0
	s_cmp_gt_u32 s76, 29
	s_cbranch_scc0 .Lk2_Y

; #define PG8_STAGE(bufoff, gbase, voff) do { _Pragma("unroll") for (int _i = 0; _i < 2; ++_i) \
;         __builtin_amdgcn_global_load_lds((const unsigned*)((const char*)(gbase) + (voff)[_i]), (PG8_LAS unsigned*)(lds + (bufoff) + ldsw + _i * 8192), 16, 0, 0); } while (0)
; #define PG8_LDA(dst, b, h) do { _Pragma("unroll") for (int m = 0; m < 4; ++m) _Pragma("unroll") for (int k = 0; k < 2; ++k) dst[m][k] = *(const PG8_LAS bf16x8*)(lds + PG8_SA(b, h) + aoff + m * 2048 + k * 1024); } while (0)
; #define PG8_WAIT_V(n) asm volatile("s_waitcnt vmcnt(" #n ")" ::: "memory")
; #define PG8_WAIT_L(n) asm volatile("s_waitcnt lgkmcnt(" #n ")" ::: "memory")
; #define PG8_BAR __builtin_amdgcn_s_barrier()
; template <class Epi, class Sched, bool ALIGN_EPI = false, bool SP2 = false, bool F8 = false>
; __device__ __forceinline__ void gemm_phase(PG8_LAS unsigned char* lds, const Gemm g, const Sched& S, const Epi& E) {
;     ...
;         for (int t = 0; t < nt; t += 2) {
;             const bool last = (t == nt - 2);
;             const char* a1 = cA + (size_t)(t + 1) * kstep;
;             const char* a2 = last ? nA : cA + (size_t)(t + 2) * kstep; const char* b2 = last ? nB : cB + (size_t)(t + 2) * kstep;
;             const char* a3 = a2 + kstep; const char* b3 = b2 + kstep;
;             if (last && has_next) S.a_ready(nxt);
;             if constexpr (SP2) {
;             PG8_LDB(B0, 0, 0); PG8_LDB(B1, 0, 1); PG8_SCHED; PG8_LDA(At, 0, 0); PG8_STAGE(PG8_SA(1, 1), a1 + hstepA, voffA);
;             PG8_WAIT_V(8); PG8_WAIT_L(0); PG8_BAR; PG8_MMA(0, 0, At, B0); PG8_MMA(0, 1, At, B1); PG8_BAR; PG8_SCHED;
;             PG8_LDA(At, 0, 1); PG8_STAGE(PG8_SB(0, 0), b2, voffB); PG8_STAGE(PG8_SB(0, 1), b2 + hstep, voffB); PG8_STAGE(PG8_SA(0, 0), a2, voffA);
;             PG8_WAIT_V(8); PG8_WAIT_L(0); PG8_BAR; PG8_MMA(1, 0, At, B0); PG8_MMA(1, 1, At, B1); PG8_BAR; PG8_SCHED;
;             PG8_LDB(B0, 1, 0); PG8_LDB(B1, 1, 1); PG8_SCHED; PG8_LDA(At, 1, 0); PG8_STAGE(PG8_SA(0, 1), a2 + hstepA, voffA);
;             PG8_WAIT_V(8); PG8_WAIT_L(0); PG8_BAR; PG8_MMA(0, 0, At, B0); PG8_MMA(0, 1, At, B1); PG8_BAR; PG8_SCHED;
;             PG8_LDA(At, 1, 1); PG8_STAGE(PG8_SB(1, 0), b3, voffB); PG8_STAGE(PG8_SB(1, 1), b3 + hstep, voffB); PG8_STAGE(PG8_SA(1, 0), a3, voffA);
;             PG8_WAIT_V(8); PG8_WAIT_L(0); PG8_BAR; PG8_MMA(1, 0, At, B0); PG8_MMA(1, 1, At, B1); PG8_BAR; PG8_SCHED;
.LBB0_1000:
	ds_read_b128 v[24:27], v197
	ds_read_b128 v[28:31], v197 offset:1024
	ds_read_b128 v[16:19], v197 offset:2048
	ds_read_b128 v[20:23], v197 offset:3072
	ds_read_b128 v[8:11], v198
	ds_read_b128 v[12:15], v198 offset:1024
	ds_read_b128 v[0:3], v198 offset:2048
	ds_read_b128 v[4:7], v198 offset:3072
	s_add_u32 s24, s52, 0xfff50080
	s_addc_u32 s25, s53, -1
	s_cmp_eq_u32 s67, 40
	s_cselect_b32 s57, s7, s25
	s_cselect_b32 s56, s6, s24
	s_cselect_b32 s55, s51, s66
	s_cselect_b32 s54, s50, s65
	s_add_i32 m0, s15, 0xc000
	ds_read_b128 v[176:179], v199
	ds_read_b128 v[180:183], v199 offset:1024
	ds_read_b128 v[184:187], v199 offset:2048
	ds_read_b128 v[188:191], v199 offset:3072
	ds_read_b128 v[200:203], v199 offset:4096
	ds_read_b128 v[204:207], v199 offset:5120
	ds_read_b128 v[208:211], v199 offset:6144
	ds_read_b128 v[212:215], v199 offset:7168
	global_load_lds_dwordx4 v168, s[52:53]
	s_add_i32 m0, s15, 0xe000
	s_nop 0
	global_load_lds_dwordx4 v170, s[52:53]
	s_waitcnt vmcnt(8)
	s_waitcnt lgkmcnt(0)
	s_setprio 1
	s_waitcnt lgkmcnt(0)
	v_mfma_f32_16x16x128_f8f6f4 v[156:159], v[24:31], v[176:183], v[156:159]
	v_mfma_f32_16x16x128_f8f6f4 v[152:155], v[16:23], v[176:183], v[152:155]
	v_mfma_f32_16x16x128_f8f6f4 v[140:143], v[24:31], v[184:191], v[140:143]
	v_mfma_f32_16x16x128_f8f6f4 v[136:139], v[16:23], v[184:191], v[136:139]
	v_mfma_f32_16x16x128_f8f6f4 v[124:127], v[24:31], v[200:207], v[124:127]
	v_mfma_f32_16x16x128_f8f6f4 v[120:123], v[16:23], v[200:207], v[120:123]
	v_mfma_f32_16x16x128_f8f6f4 v[108:111], v[24:31], v[208:215], v[108:111]
	v_mfma_f32_16x16x128_f8f6f4 v[104:107], v[16:23], v[208:215], v[104:107]
	s_setprio 0
	s_setprio 1
	v_mfma_f32_16x16x128_f8f6f4 v[148:151], v[8:15], v[176:183], v[148:151]
	v_mfma_f32_16x16x128_f8f6f4 v[144:147], v[0:7], v[176:183], v[144:147]
	v_mfma_f32_16x16x128_f8f6f4 v[132:135], v[8:15], v[184:191], v[132:135]
	v_mfma_f32_16x16x128_f8f6f4 v[128:131], v[0:7], v[184:191], v[128:131]
	v_mfma_f32_16x16x128_f8f6f4 v[116:119], v[8:15], v[200:207], v[116:119]
	v_mfma_f32_16x16x128_f8f6f4 v[112:115], v[0:7], v[200:207], v[112:115]
	v_mfma_f32_16x16x128_f8f6f4 v[100:103], v[8:15], v[208:215], v[100:103]
	v_mfma_f32_16x16x128_f8f6f4 v[96:99], v[0:7], v[208:215], v[96:99]
	s_setprio 0
	s_barrier
	s_add_i32 s24, s59, s14
	s_mov_b32 m0, s24
	ds_read_b128 v[184:187], v199 offset:16384
	ds_read_b128 v[188:191], v199 offset:17408
	ds_read_b128 v[200:203], v199 offset:18432
	ds_read_b128 v[204:207], v199 offset:19456
	ds_read_b128 v[208:211], v199 offset:20480
	ds_read_b128 v[212:215], v199 offset:21504
	ds_read_b128 v[218:221], v199 offset:22528
	ds_read_b128 v[222:225], v199 offset:23552
	global_load_lds_dwordx4 v162, s[54:55]
	s_add_i32 m0, s24, 0x2000
	s_add_u32 s24, s54, 0xb0000
	s_addc_u32 s25, s55, 0
	s_add_i32 s36, s60, s14
	global_load_lds_dwordx4 v166, s[54:55]
	s_mov_b32 m0, s36
	s_nop 0
	global_load_lds_dwordx4 v162, s[24:25]
	s_add_i32 m0, s36, 0x2000
	s_nop 0
	global_load_lds_dwordx4 v166, s[24:25]
	s_mov_b32 m0, s15
	s_nop 0
	global_load_lds_dwordx4 v160, s[56:57]
	s_mov_b32 m0, s21
	s_nop 0
	global_load_lds_dwordx4 v164, s[56:57]
	s_waitcnt vmcnt(8)
	s_waitcnt lgkmcnt(0)
	s_setprio 1
	s_waitcnt lgkmcnt(0)
	v_mfma_f32_16x16x128_f8f6f4 v[92:95], v[24:31], v[184:191], v[92:95]
	v_mfma_f32_16x16x128_f8f6f4 v[88:91], v[16:23], v[184:191], v[88:91]
	v_mfma_f32_16x16x128_f8f6f4 v[76:79], v[24:31], v[200:207], v[76:79]
	v_mfma_f32_16x16x128_f8f6f4 v[72:75], v[16:23], v[200:207], v[72:75]
	v_mfma_f32_16x16x128_f8f6f4 v[60:63], v[24:31], v[208:215], v[60:63]
	v_mfma_f32_16x16x128_f8f6f4 v[56:59], v[16:23], v[208:215], v[56:59]
	v_mfma_f32_16x16x128_f8f6f4 v[44:47], v[24:31], v[218:225], v[44:47]
	v_mfma_f32_16x16x128_f8f6f4 v[40:43], v[16:23], v[218:225], v[40:43]
	s_setprio 0
	s_setprio 1
	v_mfma_f32_16x16x128_f8f6f4 v[84:87], v[8:15], v[184:191], v[84:87]
	v_mfma_f32_16x16x128_f8f6f4 v[80:83], v[0:7], v[184:191], v[80:83]
	v_mfma_f32_16x16x128_f8f6f4 v[68:71], v[8:15], v[200:207], v[68:71]
	v_mfma_f32_16x16x128_f8f6f4 v[64:67], v[0:7], v[200:207], v[64:67]
	v_mfma_f32_16x16x128_f8f6f4 v[52:55], v[8:15], v[208:215], v[52:55]
	v_mfma_f32_16x16x128_f8f6f4 v[48:51], v[0:7], v[208:215], v[48:51]
	v_mfma_f32_16x16x128_f8f6f4 v[36:39], v[8:15], v[218:225], v[36:39]
	v_mfma_f32_16x16x128_f8f6f4 v[32:35], v[0:7], v[218:225], v[32:35]
	s_setprio 0
	s_barrier
	s_add_i32 s36, 0, 0x18000
	s_add_i32 s37, 0, 0x1c000
	v_add_u32_e32 v12, s36, v195
	v_add_u32_e32 v28, s37, v195
	ds_read_b128 v[0:3], v12
	ds_read_b128 v[4:7], v12 offset:1024
	ds_read_b128 v[8:11], v12 offset:2048
	ds_read_b128 v[12:15], v12 offset:3072
	ds_read_b128 v[16:19], v28
	ds_read_b128 v[20:23], v28 offset:1024
	ds_read_b128 v[24:27], v28 offset:2048
	ds_read_b128 v[28:31], v28 offset:3072
	s_add_u32 s24, s56, 0xb0000
	s_addc_u32 s25, s57, 0
	s_mov_b32 m0, s23
	ds_read_b128 v[184:187], v199 offset:32768
	ds_read_b128 v[188:191], v199 offset:33792
	ds_read_b128 v[200:203], v199 offset:34816
	ds_read_b128 v[204:207], v199 offset:35840
	ds_read_b128 v[208:211], v199 offset:36864
	ds_read_b128 v[212:215], v199 offset:37888
	ds_read_b128 v[218:221], v199 offset:38912
	ds_read_b128 v[222:225], v199 offset:39936
	global_load_lds_dwordx4 v160, s[24:25]
	s_mov_b32 m0, s26
	s_nop 0
	global_load_lds_dwordx4 v164, s[24:25]
	s_waitcnt vmcnt(8)
	s_waitcnt lgkmcnt(0)
	s_setprio 1
	s_waitcnt lgkmcnt(0)
	v_mfma_f32_16x16x128_f8f6f4 v[156:159], v[0:7], v[184:191], v[156:159]
	v_mfma_f32_16x16x128_f8f6f4 v[152:155], v[8:15], v[184:191], v[152:155]
	v_mfma_f32_16x16x128_f8f6f4 v[140:143], v[0:7], v[200:207], v[140:143]
	v_mfma_f32_16x16x128_f8f6f4 v[136:139], v[8:15], v[200:207], v[136:139]
	v_mfma_f32_16x16x128_f8f6f4 v[124:127], v[0:7], v[208:215], v[124:127]
	v_mfma_f32_16x16x128_f8f6f4 v[120:123], v[8:15], v[208:215], v[120:123]
	v_mfma_f32_16x16x128_f8f6f4 v[108:111], v[0:7], v[218:225], v[108:111]
	v_mfma_f32_16x16x128_f8f6f4 v[104:107], v[8:15], v[218:225], v[104:107]
	s_setprio 0
	s_setprio 1
	v_mfma_f32_16x16x128_f8f6f4 v[148:151], v[16:23], v[184:191], v[148:151]
	v_mfma_f32_16x16x128_f8f6f4 v[144:147], v[24:31], v[184:191], v[144:147]
	v_mfma_f32_16x16x128_f8f6f4 v[132:135], v[16:23], v[200:207], v[132:135]
	v_mfma_f32_16x16x128_f8f6f4 v[128:131], v[24:31], v[200:207], v[128:131]
	v_mfma_f32_16x16x128_f8f6f4 v[116:119], v[16:23], v[208:215], v[116:119]
	v_mfma_f32_16x16x128_f8f6f4 v[112:115], v[24:31], v[208:215], v[112:115]
	v_mfma_f32_16x16x128_f8f6f4 v[100:103], v[16:23], v[218:225], v[100:103]
	v_mfma_f32_16x16x128_f8f6f4 v[96:99], v[24:31], v[218:225], v[96:99]
	s_setprio 0
	s_barrier
; #define PG8_STAGE(bufoff, gbase, voff) do { _Pragma("unroll") for (int _i = 0; _i < 2; ++_i) \
;         __builtin_amdgcn_global_load_lds((const unsigned*)((const char*)(gbase) + (voff)[_i]), (PG8_LAS unsigned*)(lds + (bufoff) + ldsw + _i * 8192), 16, 0, 0); } while (0)
; #define PG8_LDA(dst, b, h) do { _Pragma("unroll") for (int m = 0; m < 4; ++m) _Pragma("unroll") for (int k = 0; k < 2; ++k) dst[m][k] = *(const PG8_LAS bf16x8*)(lds + PG8_SA(b, h) + aoff + m * 2048 + k * 1024); } while (0)
; #define PG8_WAIT_V(n) asm volatile("s_waitcnt vmcnt(" #n ")" ::: "memory")
; #define PG8_WAIT_L(n) asm volatile("s_waitcnt lgkmcnt(" #n ")" ::: "memory")
; #define PG8_BAR __builtin_amdgcn_s_barrier()
; template <class Epi, class Sched, bool ALIGN_EPI = false, bool SP2 = false, bool F8 = false>
; __device__ __forceinline__ void gemm_phase(PG8_LAS unsigned char* lds, const Gemm g, const Sched& S, const Epi& E) {
;     ...
;         for (int t = 0; t < nt; t += 2) {
;             const bool last = (t == nt - 2);
;             const char* a1 = cA + (size_t)(t + 1) * kstep;
;             const char* a2 = last ? nA : cA + (size_t)(t + 2) * kstep; const char* b2 = last ? nB : cB + (size_t)(t + 2) * kstep;
;             const char* a3 = a2 + kstep; const char* b3 = b2 + kstep;
;             if (last && has_next) S.a_ready(nxt);
;             if constexpr (SP2) {
;             PG8_LDB(B0, 0, 0); PG8_LDB(B1, 0, 1); PG8_SCHED; PG8_LDA(At, 0, 0); PG8_STAGE(PG8_SA(1, 1), a1 + hstepA, voffA);
;             PG8_WAIT_V(8); PG8_WAIT_L(0); PG8_BAR; PG8_MMA(0, 0, At, B0); PG8_MMA(0, 1, At, B1); PG8_BAR; PG8_SCHED;
;             PG8_LDA(At, 0, 1); PG8_STAGE(PG8_SB(0, 0), b2, voffB); PG8_STAGE(PG8_SB(0, 1), b2 + hstep, voffB); PG8_STAGE(PG8_SA(0, 0), a2, voffA);
;             PG8_WAIT_V(8); PG8_WAIT_L(0); PG8_BAR; PG8_MMA(1, 0, At, B0); PG8_MMA(1, 1, At, B1); PG8_BAR; PG8_SCHED;
;             PG8_LDB(B0, 1, 0); PG8_LDB(B1, 1, 1); PG8_SCHED; PG8_LDA(At, 1, 0); PG8_STAGE(PG8_SA(0, 1), a2 + hstepA, voffA);
;             PG8_WAIT_V(8); PG8_WAIT_L(0); PG8_BAR; PG8_MMA(0, 0, At, B0); PG8_MMA(0, 1, At, B1); PG8_BAR; PG8_SCHED;
;             PG8_LDA(At, 1, 1); PG8_STAGE(PG8_SB(1, 0), b3, voffB); PG8_STAGE(PG8_SB(1, 1), b3 + hstep, voffB); PG8_STAGE(PG8_SA(1, 0), a3, voffA);
;             PG8_WAIT_V(8); PG8_WAIT_L(0); PG8_BAR; PG8_MMA(1, 0, At, B0); PG8_MMA(1, 1, At, B1); PG8_BAR; PG8_SCHED;
	s_add_i32 s24, s36, s14
	s_mov_b32 m0, s24
	ds_read_b128 v[184:187], v199 offset:49152
	ds_read_b128 v[188:191], v199 offset:50176
	ds_read_b128 v[200:203], v199 offset:51200
	ds_read_b128 v[204:207], v199 offset:52224
	ds_read_b128 v[208:211], v199 offset:53248
	ds_read_b128 v[212:215], v199 offset:54272
	ds_read_b128 v[218:221], v199 offset:55296
	ds_read_b128 v[222:225], v199 offset:56320
	s_add_u32 s98, s54, 0x80
	s_addc_u32 s99, s55, 0
	global_load_lds_dwordx4 v162, s[98:99]
	s_add_i32 m0, s24, 0x2000
	s_add_u32 s24, s54, 0xb0080
	s_addc_u32 s25, s55, 0
	s_add_i32 s36, s37, s14
	s_add_u32 s100, s54, 0x80
	s_addc_u32 s101, s55, 0
	global_load_lds_dwordx4 v166, s[100:101]
	s_mov_b32 m0, s36
	s_nop 0
	global_load_lds_dwordx4 v162, s[24:25]
	s_add_i32 m0, s36, 0x2000
	s_nop 0
	global_load_lds_dwordx4 v166, s[24:25]
	s_mov_b32 m0, s33
	s_nop 0
	s_add_u32 s98, s56, 0x80
	s_addc_u32 s99, s57, 0
	global_load_lds_dwordx4 v160, s[98:99]
	s_mov_b32 m0, s43
	s_nop 0
	s_add_u32 s100, s56, 0x80
	s_addc_u32 s101, s57, 0
	global_load_lds_dwordx4 v164, s[100:101]
	s_waitcnt vmcnt(8)
	s_waitcnt lgkmcnt(0)
	s_setprio 1
	s_waitcnt lgkmcnt(0)
	v_mfma_f32_16x16x128_f8f6f4 v[92:95], v[0:7], v[184:191], v[92:95]
	v_mfma_f32_16x16x128_f8f6f4 v[88:91], v[8:15], v[184:191], v[88:91]
	v_mfma_f32_16x16x128_f8f6f4 v[76:79], v[0:7], v[200:207], v[76:79]
	v_mfma_f32_16x16x128_f8f6f4 v[72:75], v[8:15], v[200:207], v[72:75]
	v_mfma_f32_16x16x128_f8f6f4 v[60:63], v[0:7], v[208:215], v[60:63]
	v_mfma_f32_16x16x128_f8f6f4 v[56:59], v[8:15], v[208:215], v[56:59]
	v_mfma_f32_16x16x128_f8f6f4 v[44:47], v[0:7], v[218:225], v[44:47]
	v_mfma_f32_16x16x128_f8f6f4 v[40:43], v[8:15], v[218:225], v[40:43]
	s_setprio 0
	s_setprio 1
	v_mfma_f32_16x16x128_f8f6f4 v[84:87], v[16:23], v[184:191], v[84:87]
	v_mfma_f32_16x16x128_f8f6f4 v[80:83], v[24:31], v[184:191], v[80:83]
	v_mfma_f32_16x16x128_f8f6f4 v[68:71], v[16:23], v[200:207], v[68:71]
	v_mfma_f32_16x16x128_f8f6f4 v[64:67], v[24:31], v[200:207], v[64:67]
	v_mfma_f32_16x16x128_f8f6f4 v[52:55], v[16:23], v[208:215], v[52:55]
	v_mfma_f32_16x16x128_f8f6f4 v[48:51], v[24:31], v[208:215], v[48:51]
	v_mfma_f32_16x16x128_f8f6f4 v[36:39], v[16:23], v[218:225], v[36:39]
	v_mfma_f32_16x16x128_f8f6f4 v[32:35], v[24:31], v[218:225], v[32:35]
	s_setprio 0
	s_barrier
	s_add_i32 s67, s67, 2
	s_add_u32 s52, s52, 0x100
	s_addc_u32 s53, s53, 0
	s_add_u32 s65, s65, 0x100
	s_addc_u32 s66, s66, 0
	s_cmp_gt_u32 s67, 41
	s_cbranch_scc0 .LBB0_1000
	s_branch .Lk4_exit
.Lk4_Y:
	ds_read_b128 v[24:27], v197
	ds_read_b128 v[28:31], v197 offset:1024
	ds_read_b128 v[16:19], v197 offset:2048
	ds_read_b128 v[20:23], v197 offset:3072
	ds_read_b128 v[8:11], v198
	ds_read_b128 v[12:15], v198 offset:1024
	ds_read_b128 v[0:3], v198 offset:2048
	ds_read_b128 v[4:7], v198 offset:3072
	s_add_u32 s24, s52, 0xfff50080
	s_addc_u32 s25, s53, -1
	s_cmp_eq_u32 s67, 40
	s_cselect_b32 s57, s7, s25
	s_cselect_b32 s56, s6, s24
	s_cselect_b32 s55, s51, s66
	s_cselect_b32 s54, s50, s65
	s_add_i32 m0, s15, 0xc000
	ds_read_b128 v[176:179], v199
	ds_read_b128 v[180:183], v199 offset:1024
	ds_read_b128 v[184:187], v199 offset:2048
	ds_read_b128 v[188:191], v199 offset:3072
	ds_read_b128 v[200:203], v199 offset:4096
	ds_read_b128 v[204:207], v199 offset:5120
	ds_read_b128 v[208:211], v199 offset:6144
	ds_read_b128 v[212:215], v199 offset:7168
	global_load_lds_dwordx4 v168, s[52:53]
	s_add_i32 m0, s15, 0xe000
	s_nop 0
	global_load_lds_dwordx4 v170, s[52:53]
	s_waitcnt vmcnt(8)
	s_waitcnt lgkmcnt(0)
	s_barrier
	s_setprio 3
	s_waitcnt lgkmcnt(0)
	v_mfma_f32_16x16x128_f8f6f4 v[156:159], v[24:31], v[176:183], v[156:159]
	v_mfma_f32_16x16x128_f8f6f4 v[152:155], v[16:23], v[176:183], v[152:155]
	v_mfma_f32_16x16x128_f8f6f4 v[140:143], v[24:31], v[184:191], v[140:143]
	v_mfma_f32_16x16x128_f8f6f4 v[136:139], v[16:23], v[184:191], v[136:139]
	v_mfma_f32_16x16x128_f8f6f4 v[124:127], v[24:31], v[200:207], v[124:127]
	v_mfma_f32_16x16x128_f8f6f4 v[120:123], v[16:23], v[200:207], v[120:123]
	v_mfma_f32_16x16x128_f8f6f4 v[108:111], v[24:31], v[208:215], v[108:111]
	v_mfma_f32_16x16x128_f8f6f4 v[104:107], v[16:23], v[208:215], v[104:107]
	s_setprio 0
	s_setprio 3
	v_mfma_f32_16x16x128_f8f6f4 v[148:151], v[8:15], v[176:183], v[148:151]
	v_mfma_f32_16x16x128_f8f6f4 v[144:147], v[0:7], v[176:183], v[144:147]
	v_mfma_f32_16x16x128_f8f6f4 v[132:135], v[8:15], v[184:191], v[132:135]
	v_mfma_f32_16x16x128_f8f6f4 v[128:131], v[0:7], v[184:191], v[128:131]
	v_mfma_f32_16x16x128_f8f6f4 v[116:119], v[8:15], v[200:207], v[116:119]
	v_mfma_f32_16x16x128_f8f6f4 v[112:115], v[0:7], v[200:207], v[112:115]
	v_mfma_f32_16x16x128_f8f6f4 v[100:103], v[8:15], v[208:215], v[100:103]
	v_mfma_f32_16x16x128_f8f6f4 v[96:99], v[0:7], v[208:215], v[96:99]
	s_setprio 0
	s_add_i32 s24, s59, s14
	s_mov_b32 m0, s24
	ds_read_b128 v[184:187], v199 offset:16384
	ds_read_b128 v[188:191], v199 offset:17408
	ds_read_b128 v[200:203], v199 offset:18432
	ds_read_b128 v[204:207], v199 offset:19456
	ds_read_b128 v[208:211], v199 offset:20480
	ds_read_b128 v[212:215], v199 offset:21504
	ds_read_b128 v[218:221], v199 offset:22528
	ds_read_b128 v[222:225], v199 offset:23552
	global_load_lds_dwordx4 v162, s[54:55]
	s_add_i32 m0, s24, 0x2000
	s_add_u32 s24, s54, 0xb0000
	s_addc_u32 s25, s55, 0
	s_add_i32 s36, s60, s14
	global_load_lds_dwordx4 v166, s[54:55]
	s_mov_b32 m0, s36
	s_nop 0
	global_load_lds_dwordx4 v162, s[24:25]
	s_add_i32 m0, s36, 0x2000
	s_nop 0
	global_load_lds_dwordx4 v166, s[24:25]
	s_mov_b32 m0, s15
	s_nop 0
	global_load_lds_dwordx4 v160, s[56:57]
	s_mov_b32 m0, s21
	s_nop 0
	global_load_lds_dwordx4 v164, s[56:57]
	s_waitcnt vmcnt(8)
	s_waitcnt lgkmcnt(0)
	s_barrier
; #define PG8_STAGE(bufoff, gbase, voff) do { _Pragma("unroll") for (int _i = 0; _i < 2; ++_i) \
;         __builtin_amdgcn_global_load_lds((const unsigned*)((const char*)(gbase) + (voff)[_i]), (PG8_LAS unsigned*)(lds + (bufoff) + ldsw + _i * 8192), 16, 0, 0); } while (0)
; #define PG8_LDA(dst, b, h) do { _Pragma("unroll") for (int m = 0; m < 4; ++m) _Pragma("unroll") for (int k = 0; k < 2; ++k) dst[m][k] = *(const PG8_LAS bf16x8*)(lds + PG8_SA(b, h) + aoff + m * 2048 + k * 1024); } while (0)
; #define PG8_LDB(dst, b, h) do { _Pragma("unroll") for (int n = 0; n < 2; ++n) _Pragma("unroll") for (int k = 0; k < 2; ++k) dst[n][k] = *(const PG8_LAS bf16x8*)(lds + PG8_SB(b, h) + boff + n * 2048 + k * 1024); } while (0)
; #define PG8_WAIT_V(n) asm volatile("s_waitcnt vmcnt(" #n ")" ::: "memory")
; #define PG8_WAIT_L(n) asm volatile("s_waitcnt lgkmcnt(" #n ")" ::: "memory")
; #define PG8_BAR __builtin_amdgcn_s_barrier()
; #define PG8_SCHED __builtin_amdgcn_sched_barrier(0)
; template <class Epi, class Sched, bool ALIGN_EPI = false, bool SP2 = false, bool F8 = false>
; __device__ __forceinline__ void gemm_phase(PG8_LAS unsigned char* lds, const Gemm g, const Sched& S, const Epi& E) {
;     ...
;             PG8_LDB(B0, 0, 0); PG8_LDB(B1, 0, 1); PG8_SCHED; PG8_LDA(At, 0, 0); PG8_STAGE(PG8_SA(1, 1), a1 + hstepA, voffA);
;             PG8_WAIT_V(8); PG8_WAIT_L(0); PG8_BAR; PG8_MMA(0, 0, At, B0); PG8_MMA(0, 1, At, B1); PG8_BAR; PG8_SCHED;
;             PG8_LDA(At, 0, 1); PG8_STAGE(PG8_SB(0, 0), b2, voffB); PG8_STAGE(PG8_SB(0, 1), b2 + hstep, voffB); PG8_STAGE(PG8_SA(0, 0), a2, voffA);
;             PG8_WAIT_V(8); PG8_WAIT_L(0); PG8_BAR; PG8_MMA(1, 0, At, B0); PG8_MMA(1, 1, At, B1); PG8_BAR; PG8_SCHED;
;             PG8_LDB(B0, 1, 0); PG8_LDB(B1, 1, 1); PG8_SCHED; PG8_LDA(At, 1, 0); PG8_STAGE(PG8_SA(0, 1), a2 + hstepA, voffA);
;             PG8_WAIT_V(8); PG8_WAIT_L(0); PG8_BAR; PG8_MMA(0, 0, At, B0); PG8_MMA(0, 1, At, B1); PG8_BAR; PG8_SCHED;
;             PG8_LDA(At, 1, 1); PG8_STAGE(PG8_SB(1, 0), b3, voffB); PG8_STAGE(PG8_SB(1, 1), b3 + hstep, voffB); PG8_STAGE(PG8_SA(1, 0), a3, voffA);
;             PG8_WAIT_V(8); PG8_WAIT_L(0); PG8_BAR; PG8_MMA(1, 0, At, B0); PG8_MMA(1, 1, At, B1); PG8_BAR; PG8_SCHED;
	s_setprio 3
	s_waitcnt lgkmcnt(0)
	v_mfma_f32_16x16x128_f8f6f4 v[92:95], v[24:31], v[184:191], v[92:95]
	v_mfma_f32_16x16x128_f8f6f4 v[88:91], v[16:23], v[184:191], v[88:91]
	v_mfma_f32_16x16x128_f8f6f4 v[76:79], v[24:31], v[200:207], v[76:79]
	v_mfma_f32_16x16x128_f8f6f4 v[72:75], v[16:23], v[200:207], v[72:75]
	v_mfma_f32_16x16x128_f8f6f4 v[60:63], v[24:31], v[208:215], v[60:63]
	v_mfma_f32_16x16x128_f8f6f4 v[56:59], v[16:23], v[208:215], v[56:59]
	v_mfma_f32_16x16x128_f8f6f4 v[44:47], v[24:31], v[218:225], v[44:47]
	v_mfma_f32_16x16x128_f8f6f4 v[40:43], v[16:23], v[218:225], v[40:43]
	s_setprio 0
	s_setprio 3
	v_mfma_f32_16x16x128_f8f6f4 v[84:87], v[8:15], v[184:191], v[84:87]
	v_mfma_f32_16x16x128_f8f6f4 v[80:83], v[0:7], v[184:191], v[80:83]
	v_mfma_f32_16x16x128_f8f6f4 v[68:71], v[8:15], v[200:207], v[68:71]
	v_mfma_f32_16x16x128_f8f6f4 v[64:67], v[0:7], v[200:207], v[64:67]
	v_mfma_f32_16x16x128_f8f6f4 v[52:55], v[8:15], v[208:215], v[52:55]
	v_mfma_f32_16x16x128_f8f6f4 v[48:51], v[0:7], v[208:215], v[48:51]
	v_mfma_f32_16x16x128_f8f6f4 v[36:39], v[8:15], v[218:225], v[36:39]
	v_mfma_f32_16x16x128_f8f6f4 v[32:35], v[0:7], v[218:225], v[32:35]
	s_setprio 0
	s_add_i32 s36, 0, 0x18000
	s_add_i32 s37, 0, 0x1c000
	v_add_u32_e32 v12, s36, v195
	v_add_u32_e32 v28, s37, v195
	ds_read_b128 v[0:3], v12
	ds_read_b128 v[4:7], v12 offset:1024
	ds_read_b128 v[8:11], v12 offset:2048
	ds_read_b128 v[12:15], v12 offset:3072
	ds_read_b128 v[16:19], v28
	ds_read_b128 v[20:23], v28 offset:1024
	ds_read_b128 v[24:27], v28 offset:2048
	ds_read_b128 v[28:31], v28 offset:3072
	s_add_u32 s24, s56, 0xb0000
	s_addc_u32 s25, s57, 0
	s_mov_b32 m0, s23
	ds_read_b128 v[184:187], v199 offset:32768
	ds_read_b128 v[188:191], v199 offset:33792
	ds_read_b128 v[200:203], v199 offset:34816
	ds_read_b128 v[204:207], v199 offset:35840
	ds_read_b128 v[208:211], v199 offset:36864
	ds_read_b128 v[212:215], v199 offset:37888
	ds_read_b128 v[218:221], v199 offset:38912
	ds_read_b128 v[222:225], v199 offset:39936
	global_load_lds_dwordx4 v160, s[24:25]
	s_mov_b32 m0, s26
	s_nop 0
	global_load_lds_dwordx4 v164, s[24:25]
	s_waitcnt vmcnt(8)
	s_waitcnt lgkmcnt(0)
	s_barrier
	s_setprio 3
	s_waitcnt lgkmcnt(0)
	v_mfma_f32_16x16x128_f8f6f4 v[156:159], v[0:7], v[184:191], v[156:159]
	v_mfma_f32_16x16x128_f8f6f4 v[152:155], v[8:15], v[184:191], v[152:155]
	v_mfma_f32_16x16x128_f8f6f4 v[140:143], v[0:7], v[200:207], v[140:143]
	v_mfma_f32_16x16x128_f8f6f4 v[136:139], v[8:15], v[200:207], v[136:139]
	v_mfma_f32_16x16x128_f8f6f4 v[124:127], v[0:7], v[208:215], v[124:127]
	v_mfma_f32_16x16x128_f8f6f4 v[120:123], v[8:15], v[208:215], v[120:123]
	v_mfma_f32_16x16x128_f8f6f4 v[108:111], v[0:7], v[218:225], v[108:111]
	v_mfma_f32_16x16x128_f8f6f4 v[104:107], v[8:15], v[218:225], v[104:107]
	s_setprio 0
	s_setprio 3
	v_mfma_f32_16x16x128_f8f6f4 v[148:151], v[16:23], v[184:191], v[148:151]
	v_mfma_f32_16x16x128_f8f6f4 v[144:147], v[24:31], v[184:191], v[144:147]
	v_mfma_f32_16x16x128_f8f6f4 v[132:135], v[16:23], v[200:207], v[132:135]
	v_mfma_f32_16x16x128_f8f6f4 v[128:131], v[24:31], v[200:207], v[128:131]
	v_mfma_f32_16x16x128_f8f6f4 v[116:119], v[16:23], v[208:215], v[116:119]
	v_mfma_f32_16x16x128_f8f6f4 v[112:115], v[24:31], v[208:215], v[112:115]
	v_mfma_f32_16x16x128_f8f6f4 v[100:103], v[16:23], v[218:225], v[100:103]
	v_mfma_f32_16x16x128_f8f6f4 v[96:99], v[24:31], v[218:225], v[96:99]
	s_setprio 0
	s_add_i32 s24, s36, s14
	s_mov_b32 m0, s24
	ds_read_b128 v[184:187], v199 offset:49152
	ds_read_b128 v[188:191], v199 offset:50176
	ds_read_b128 v[200:203], v199 offset:51200
	ds_read_b128 v[204:207], v199 offset:52224
	ds_read_b128 v[208:211], v199 offset:53248
	ds_read_b128 v[212:215], v199 offset:54272
	ds_read_b128 v[218:221], v199 offset:55296
	ds_read_b128 v[222:225], v199 offset:56320
	s_add_u32 s98, s54, 0x80
	s_addc_u32 s99, s55, 0
	global_load_lds_dwordx4 v162, s[98:99]
	s_add_i32 m0, s24, 0x2000
	s_add_u32 s24, s54, 0xb0080
	s_addc_u32 s25, s55, 0
	s_add_i32 s36, s37, s14
	s_add_u32 s100, s54, 0x80
	s_addc_u32 s101, s55, 0
	global_load_lds_dwordx4 v166, s[100:101]
	s_mov_b32 m0, s36
	s_nop 0
	global_load_lds_dwordx4 v162, s[24:25]
	s_add_i32 m0, s36, 0x2000
	s_nop 0
	global_load_lds_dwordx4 v166, s[24:25]
	s_mov_b32 m0, s33
	s_nop 0
	s_add_u32 s98, s56, 0x80
	s_addc_u32 s99, s57, 0
	global_load_lds_dwordx4 v160, s[98:99]
	s_mov_b32 m0, s43
	s_nop 0
	s_add_u32 s100, s56, 0x80
	s_addc_u32 s101, s57, 0
	global_load_lds_dwordx4 v164, s[100:101]
	s_waitcnt vmcnt(8)
	s_waitcnt lgkmcnt(0)
	s_barrier
	s_setprio 3
	s_waitcnt lgkmcnt(0)
	v_mfma_f32_16x16x128_f8f6f4 v[92:95], v[0:7], v[184:191], v[92:95]
	v_mfma_f32_16x16x128_f8f6f4 v[88:91], v[8:15], v[184:191], v[88:91]
	v_mfma_f32_16x16x128_f8f6f4 v[76:79], v[0:7], v[200:207], v[76:79]
	v_mfma_f32_16x16x128_f8f6f4 v[72:75], v[8:15], v[200:207], v[72:75]
	v_mfma_f32_16x16x128_f8f6f4 v[60:63], v[0:7], v[208:215], v[60:63]
	v_mfma_f32_16x16x128_f8f6f4 v[56:59], v[8:15], v[208:215], v[56:59]
	v_mfma_f32_16x16x128_f8f6f4 v[44:47], v[0:7], v[218:225], v[44:47]
	v_mfma_f32_16x16x128_f8f6f4 v[40:43], v[8:15], v[218:225], v[40:43]
	s_setprio 0
	s_setprio 3
	v_mfma_f32_16x16x128_f8f6f4 v[84:87], v[16:23], v[184:191], v[84:87]
	v_mfma_f32_16x16x128_f8f6f4 v[80:83], v[24:31], v[184:191], v[80:83]
	v_mfma_f32_16x16x128_f8f6f4 v[68:71], v[16:23], v[200:207], v[68:71]
	v_mfma_f32_16x16x128_f8f6f4 v[64:67], v[24:31], v[200:207], v[64:67]
	v_mfma_f32_16x16x128_f8f6f4 v[52:55], v[16:23], v[208:215], v[52:55]
	v_mfma_f32_16x16x128_f8f6f4 v[48:51], v[24:31], v[208:215], v[48:51]
	v_mfma_f32_16x16x128_f8f6f4 v[36:39], v[16:23], v[218:225], v[36:39]
	v_mfma_f32_16x16x128_f8f6f4 v[32:35], v[24:31], v[218:225], v[32:35]
	s_setprio 0
	s_add_i32 s67, s67, 2
	s_add_u32 s52, s52, 0x100
	s_addc_u32 s53, s53, 0
	s_add_u32 s65, s65, 0x100
	s_addc_u32 s66, s66, 0
	s_cmp_gt_u32 s67, 41
	s_cbranch_scc0 .Lk4_Y
